# K-loops: the s_setprio 0 / s_setprio 1 pair in the middle of every MFMA block deleted (priority stays raised across the whole block)
# speedup vs baseline: 1.0009x; 1.0009x over previous
; #define PG8_STAGE(bufoff, gbase, voff) do { _Pragma("unroll") for (int _i = 0; _i < 2; ++_i) \
;         __builtin_amdgcn_global_load_lds((const unsigned*)((const char*)(gbase) + (voff)[_i]), (LAS unsigned*)(lds + (bufoff) + ldsw + _i * 8192), 16, 0, 0); } while (0)
; #define PG8_LDA(dst, b, h) do { _Pragma("unroll") for (int m = 0; m < 4; ++m) _Pragma("unroll") for (int k = 0; k < 2; ++k) dst[m][k] = *(const LAS bf16x8*)(lds + PG8_SA(b, h) + aoff + m * 2048 + k * 1024); } while (0)
; #define PG8_MMA(ai, bj, At, Bt) do { __builtin_amdgcn_s_setprio(1); _Pragma("unroll") for (int m = 0; m < 4; ++m) _Pragma("unroll") for (int n = 0; n < 2; ++n) _Pragma("unroll") for (int k = 0; k < 2; ++k) \
;         acc[ai][bj][m][n] = __builtin_amdgcn_mfma_f32_16x16x32_bf16(Bt[n][k], At[m][k], acc[ai][bj][m][n], 0, 0, 0); __builtin_amdgcn_s_setprio(0); } while (0)
; #define PG8_WAIT_V(n) asm volatile("s_waitcnt vmcnt(" #n ")" ::: "memory")
; #define PG8_WAIT_L(n) asm volatile("s_waitcnt lgkmcnt(" #n ")" ::: "memory")
; #define PG8_BAR __builtin_amdgcn_s_barrier()
; #define PG8_SCHED __builtin_amdgcn_sched_barrier(0)
; template <class Epi>
; __device__ __forceinline__ void gemm_phase(LAS unsigned char* lds, const Gemm g, const Epi& E) {
;     ...
;             PG8_WAIT_V(8); PG8_WAIT_L(0); PG8_BAR; PG8_MMA(0, 0, At, B0); PG8_MMA(0, 1, At, B1); PG8_BAR; PG8_SCHED;
;             PG8_LDA(At, 0, 1); PG8_STAGE(PG8_SB(0, 0), b2, voffA); PG8_STAGE(PG8_SB(0, 1), b2 + hstep, voffA); PG8_STAGE(PG8_SA(0, 0), a2, voffA);
.Lrw1a_d:
	s_waitcnt lgkmcnt(0)
	s_barrier
	s_setprio 1
	s_waitcnt lgkmcnt(0)
	v_mfma_f32_16x16x32_bf16 v[122:125], v[130:133], v[202:205], v[122:125]
	v_mfma_f32_16x16x32_bf16 v[126:129], v[152:155], v[202:205], v[126:129]
	v_mfma_f32_16x16x32_bf16 v[106:109], v[130:133], v[210:213], v[106:109]
	v_mfma_f32_16x16x32_bf16 v[110:113], v[152:155], v[210:213], v[110:113]
	v_mfma_f32_16x16x32_bf16 v[90:93], v[130:133], v[218:221], v[90:93]
	v_mfma_f32_16x16x32_bf16 v[94:97], v[152:155], v[218:221], v[94:97]
	v_mfma_f32_16x16x32_bf16 v[74:77], v[130:133], v[226:229], v[74:77]
	v_mfma_f32_16x16x32_bf16 v[78:81], v[152:155], v[226:229], v[78:81]
	v_mfma_f32_16x16x32_bf16 v[122:125], v[134:137], v[206:209], v[122:125]
	v_mfma_f32_16x16x32_bf16 v[126:129], v[156:159], v[206:209], v[126:129]
	v_mfma_f32_16x16x32_bf16 v[106:109], v[134:137], v[214:217], v[106:109]
	v_mfma_f32_16x16x32_bf16 v[110:113], v[156:159], v[214:217], v[110:113]
	v_mfma_f32_16x16x32_bf16 v[90:93], v[134:137], v[222:225], v[90:93]
	v_mfma_f32_16x16x32_bf16 v[94:97], v[156:159], v[222:225], v[94:97]
	v_mfma_f32_16x16x32_bf16 v[74:77], v[134:137], v[230:233], v[74:77]
	v_mfma_f32_16x16x32_bf16 v[78:81], v[156:159], v[230:233], v[78:81]
	v_mfma_f32_16x16x32_bf16 v[114:117], v[160:163], v[202:205], v[114:117]
	v_mfma_f32_16x16x32_bf16 v[118:121], v[194:197], v[202:205], v[118:121]
	v_mfma_f32_16x16x32_bf16 v[98:101], v[160:163], v[210:213], v[98:101]
	v_mfma_f32_16x16x32_bf16 v[102:105], v[194:197], v[210:213], v[102:105]
	v_mfma_f32_16x16x32_bf16 v[82:85], v[160:163], v[218:221], v[82:85]
	v_mfma_f32_16x16x32_bf16 v[86:89], v[194:197], v[218:221], v[86:89]
	v_mfma_f32_16x16x32_bf16 v[66:69], v[160:163], v[226:229], v[66:69]
	v_mfma_f32_16x16x32_bf16 v[70:73], v[194:197], v[226:229], v[70:73]
	v_mfma_f32_16x16x32_bf16 v[114:117], v[190:193], v[206:209], v[114:117]
	v_mfma_f32_16x16x32_bf16 v[118:121], v[198:201], v[206:209], v[118:121]
	v_mfma_f32_16x16x32_bf16 v[98:101], v[190:193], v[214:217], v[98:101]
	v_mfma_f32_16x16x32_bf16 v[102:105], v[198:201], v[214:217], v[102:105]
	v_mfma_f32_16x16x32_bf16 v[82:85], v[190:193], v[222:225], v[82:85]
	v_mfma_f32_16x16x32_bf16 v[86:89], v[198:201], v[222:225], v[86:89]
	v_mfma_f32_16x16x32_bf16 v[66:69], v[190:193], v[230:233], v[66:69]
	v_mfma_f32_16x16x32_bf16 v[70:73], v[198:201], v[230:233], v[70:73]
	s_setprio 0
	s_barrier
	s_add_i32 s79, s21, s26
	v_lshl_add_u64 v[164:165], s[4:5], 0, v[0:1]
	s_mov_b32 m0, s79
	ds_read_b128 v[202:205], v167 offset:16384
	ds_read_b128 v[206:209], v167 offset:17408
	ds_read_b128 v[210:213], v167 offset:18432
	ds_read_b128 v[214:217], v167 offset:19456
	ds_read_b128 v[218:221], v167 offset:20480
	ds_read_b128 v[222:225], v167 offset:21504
	ds_read_b128 v[226:229], v167 offset:22528
	ds_read_b128 v[230:233], v167 offset:23552
	global_load_lds_dwordx4 v[164:165], off
	s_add_i32 m0, s79, 0x2000
	s_add_u32 vcc_lo, s4, 0x40000
	v_lshl_add_u64 v[168:169], s[4:5], 0, v[146:147]
	s_addc_u32 vcc_hi, s5, 0
	s_add_i32 s25, s25, s26
	global_load_lds_dwordx4 v[168:169], off
	v_lshl_add_u64 v[234:235], vcc, 0, v[0:1]
	s_mov_b32 m0, s25
	v_lshl_add_u64 v[236:237], s[10:11], 0, v[146:147]
	global_load_lds_dwordx4 v[234:235], off
	v_lshl_add_u64 v[234:235], vcc, 0, v[146:147]
	s_add_i32 m0, s25, 0x2000
	s_nop 0
	global_load_lds_dwordx4 v[234:235], off
	v_lshl_add_u64 v[234:235], s[10:11], 0, v[0:1]
	s_mov_b32 m0, s53
	s_nop 0
	global_load_lds_dwordx4 v[234:235], off
	s_mov_b32 m0, s73
	s_nop 0
	global_load_lds_dwordx4 v[236:237], off
	s_cmp_eq_u32 s32, 1
	s_cbranch_scc1 .Lrw1b_1
	s_cmp_eq_u32 s32, 2
	s_cbranch_scc1 .Lrw1b_2
	s_waitcnt vmcnt(63)
	s_branch .Lrw1b_d

; #define PG8_STAGE(bufoff, gbase, voff) do { _Pragma("unroll") for (int _i = 0; _i < 2; ++_i) \
;         __builtin_amdgcn_global_load_lds((const unsigned*)((const char*)(gbase) + (voff)[_i]), (LAS unsigned*)(lds + (bufoff) + ldsw + _i * 8192), 16, 0, 0); } while (0)
; #define PG8_LDA(dst, b, h) do { _Pragma("unroll") for (int m = 0; m < 4; ++m) _Pragma("unroll") for (int k = 0; k < 2; ++k) dst[m][k] = *(const LAS bf16x8*)(lds + PG8_SA(b, h) + aoff + m * 2048 + k * 1024); } while (0)
; #define PG8_LDB(dst, b, h) do { _Pragma("unroll") for (int n = 0; n < 2; ++n) _Pragma("unroll") for (int k = 0; k < 2; ++k) dst[n][k] = *(const LAS bf16x8*)(lds + PG8_SB(b, h) + boff + n * 2048 + k * 1024); } while (0)
; #define PG8_MMA(ai, bj, At, Bt) do { __builtin_amdgcn_s_setprio(1); _Pragma("unroll") for (int m = 0; m < 4; ++m) _Pragma("unroll") for (int n = 0; n < 2; ++n) _Pragma("unroll") for (int k = 0; k < 2; ++k) \
;         acc[ai][bj][m][n] = __builtin_amdgcn_mfma_f32_16x16x32_bf16(Bt[n][k], At[m][k], acc[ai][bj][m][n], 0, 0, 0); __builtin_amdgcn_s_setprio(0); } while (0)
; #define PG8_WAIT_V(n) asm volatile("s_waitcnt vmcnt(" #n ")" ::: "memory")
; #define PG8_WAIT_L(n) asm volatile("s_waitcnt lgkmcnt(" #n ")" ::: "memory")
; #define PG8_BAR __builtin_amdgcn_s_barrier()
; #define PG8_SCHED __builtin_amdgcn_sched_barrier(0)
; template <class Epi>
; __device__ __forceinline__ void gemm_phase(LAS unsigned char* lds, const Gemm g, const Epi& E) {
;     ...
;             PG8_WAIT_V(8); PG8_WAIT_L(0); PG8_BAR; PG8_MMA(1, 0, At, B0); PG8_MMA(1, 1, At, B1); PG8_BAR; PG8_SCHED;
;             PG8_LDB(B0, 1, 0); PG8_LDB(B1, 1, 1); PG8_SCHED; PG8_LDA(At, 1, 0); PG8_STAGE(PG8_SA(0, 1), a2 + hstep, voffA);
;             PG8_WAIT_V(8); PG8_WAIT_L(0); PG8_BAR; PG8_MMA(0, 0, At, B0); PG8_MMA(0, 1, At, B1); PG8_BAR; PG8_SCHED;
.Lrw1b_d:
	s_mov_b32 s32, 0
	s_waitcnt lgkmcnt(0)
	s_barrier
	s_setprio 1
	s_waitcnt lgkmcnt(0)
	v_mfma_f32_16x16x32_bf16 v[58:61], v[130:133], v[202:205], v[58:61]
	v_mfma_f32_16x16x32_bf16 v[62:65], v[152:155], v[202:205], v[62:65]
	v_mfma_f32_16x16x32_bf16 v[42:45], v[130:133], v[210:213], v[42:45]
	v_mfma_f32_16x16x32_bf16 v[46:49], v[152:155], v[210:213], v[46:49]
	v_mfma_f32_16x16x32_bf16 v[26:29], v[130:133], v[218:221], v[26:29]
	v_mfma_f32_16x16x32_bf16 v[30:33], v[152:155], v[218:221], v[30:33]
	v_mfma_f32_16x16x32_bf16 v[10:13], v[130:133], v[226:229], v[10:13]
	v_mfma_f32_16x16x32_bf16 v[14:17], v[152:155], v[226:229], v[14:17]
	v_mfma_f32_16x16x32_bf16 v[58:61], v[134:137], v[206:209], v[58:61]
	v_mfma_f32_16x16x32_bf16 v[62:65], v[156:159], v[206:209], v[62:65]
	v_mfma_f32_16x16x32_bf16 v[42:45], v[134:137], v[214:217], v[42:45]
	v_mfma_f32_16x16x32_bf16 v[46:49], v[156:159], v[214:217], v[46:49]
	v_mfma_f32_16x16x32_bf16 v[26:29], v[134:137], v[222:225], v[26:29]
	v_mfma_f32_16x16x32_bf16 v[30:33], v[156:159], v[222:225], v[30:33]
	v_mfma_f32_16x16x32_bf16 v[10:13], v[134:137], v[230:233], v[10:13]
	v_mfma_f32_16x16x32_bf16 v[14:17], v[156:159], v[230:233], v[14:17]
	v_mfma_f32_16x16x32_bf16 v[50:53], v[160:163], v[202:205], v[50:53]
	v_mfma_f32_16x16x32_bf16 v[54:57], v[194:197], v[202:205], v[54:57]
	v_mfma_f32_16x16x32_bf16 v[34:37], v[160:163], v[210:213], v[34:37]
	v_mfma_f32_16x16x32_bf16 v[38:41], v[194:197], v[210:213], v[38:41]
	v_mfma_f32_16x16x32_bf16 v[18:21], v[160:163], v[218:221], v[18:21]
	v_mfma_f32_16x16x32_bf16 v[22:25], v[194:197], v[218:221], v[22:25]
	v_mfma_f32_16x16x32_bf16 v[6:9], v[160:163], v[226:229], v[6:9]
	v_mfma_f32_16x16x32_bf16 v[2:5], v[194:197], v[226:229], v[2:5]
	v_mfma_f32_16x16x32_bf16 v[50:53], v[190:193], v[206:209], v[50:53]
	v_mfma_f32_16x16x32_bf16 v[54:57], v[198:201], v[206:209], v[54:57]
	v_mfma_f32_16x16x32_bf16 v[34:37], v[190:193], v[214:217], v[34:37]
	v_mfma_f32_16x16x32_bf16 v[38:41], v[198:201], v[214:217], v[38:41]
	v_mfma_f32_16x16x32_bf16 v[18:21], v[190:193], v[222:225], v[18:21]
	v_mfma_f32_16x16x32_bf16 v[22:25], v[198:201], v[222:225], v[22:25]
	v_mfma_f32_16x16x32_bf16 v[6:9], v[190:193], v[230:233], v[6:9]
	v_mfma_f32_16x16x32_bf16 v[2:5], v[198:201], v[230:233], v[2:5]
	s_setprio 0
	s_barrier
	s_add_i32 s25, 0, 0x18000
	s_add_i32 s79, 0, 0x1c000
	v_add_u32_e32 v156, s25, v166
	v_add_u32_e32 v189, s79, v166
	ds_read_b128 v[130:133], v156
	ds_read_b128 v[134:137], v156 offset:1024
	ds_read_b128 v[152:155], v156 offset:2048
	ds_read_b128 v[156:159], v156 offset:3072
	ds_read_b128 v[160:163], v189
	ds_read_b128 v[190:193], v189 offset:1024
	ds_read_b128 v[194:197], v189 offset:2048
	ds_read_b128 v[198:201], v189 offset:3072
	s_add_u32 s10, s10, 0x40000
	s_addc_u32 s11, s11, 0
	s_mov_b32 m0, s76
	v_lshl_add_u64 v[238:239], s[10:11], 0, v[0:1]
	ds_read_b128 v[202:205], v167 offset:32768
	ds_read_b128 v[206:209], v167 offset:33792
	ds_read_b128 v[210:213], v167 offset:34816
	ds_read_b128 v[214:217], v167 offset:35840
	ds_read_b128 v[218:221], v167 offset:36864
	ds_read_b128 v[222:225], v167 offset:37888
	ds_read_b128 v[226:229], v167 offset:38912
	ds_read_b128 v[230:233], v167 offset:39936
	global_load_lds_dwordx4 v[238:239], off
	v_lshl_add_u64 v[238:239], s[10:11], 0, v[146:147]
	s_mov_b32 m0, s77
	s_nop 0
	global_load_lds_dwordx4 v[238:239], off
	s_waitcnt vmcnt(8)
	s_waitcnt lgkmcnt(0)
	s_barrier
	s_setprio 1
	s_waitcnt lgkmcnt(0)
	v_mfma_f32_16x16x32_bf16 v[122:125], v[130:133], v[202:205], v[122:125]
	v_mfma_f32_16x16x32_bf16 v[126:129], v[152:155], v[202:205], v[126:129]
	v_mfma_f32_16x16x32_bf16 v[106:109], v[130:133], v[210:213], v[106:109]
	v_mfma_f32_16x16x32_bf16 v[110:113], v[152:155], v[210:213], v[110:113]
	v_mfma_f32_16x16x32_bf16 v[90:93], v[130:133], v[218:221], v[90:93]
	v_mfma_f32_16x16x32_bf16 v[94:97], v[152:155], v[218:221], v[94:97]
	v_mfma_f32_16x16x32_bf16 v[74:77], v[130:133], v[226:229], v[74:77]
	v_mfma_f32_16x16x32_bf16 v[78:81], v[152:155], v[226:229], v[78:81]
	v_mfma_f32_16x16x32_bf16 v[122:125], v[134:137], v[206:209], v[122:125]
	v_mfma_f32_16x16x32_bf16 v[126:129], v[156:159], v[206:209], v[126:129]
	v_mfma_f32_16x16x32_bf16 v[106:109], v[134:137], v[214:217], v[106:109]
	v_mfma_f32_16x16x32_bf16 v[110:113], v[156:159], v[214:217], v[110:113]
	v_mfma_f32_16x16x32_bf16 v[90:93], v[134:137], v[222:225], v[90:93]
	v_mfma_f32_16x16x32_bf16 v[94:97], v[156:159], v[222:225], v[94:97]
	v_mfma_f32_16x16x32_bf16 v[74:77], v[134:137], v[230:233], v[74:77]
	v_mfma_f32_16x16x32_bf16 v[78:81], v[156:159], v[230:233], v[78:81]
	v_mfma_f32_16x16x32_bf16 v[114:117], v[160:163], v[202:205], v[114:117]
	v_mfma_f32_16x16x32_bf16 v[118:121], v[194:197], v[202:205], v[118:121]
	v_mfma_f32_16x16x32_bf16 v[98:101], v[160:163], v[210:213], v[98:101]
	v_mfma_f32_16x16x32_bf16 v[102:105], v[194:197], v[210:213], v[102:105]
	v_mfma_f32_16x16x32_bf16 v[82:85], v[160:163], v[218:221], v[82:85]
	v_mfma_f32_16x16x32_bf16 v[86:89], v[194:197], v[218:221], v[86:89]
	v_mfma_f32_16x16x32_bf16 v[66:69], v[160:163], v[226:229], v[66:69]
	v_mfma_f32_16x16x32_bf16 v[70:73], v[194:197], v[226:229], v[70:73]
	v_mfma_f32_16x16x32_bf16 v[114:117], v[190:193], v[206:209], v[114:117]
	v_mfma_f32_16x16x32_bf16 v[118:121], v[198:201], v[206:209], v[118:121]
	v_mfma_f32_16x16x32_bf16 v[98:101], v[190:193], v[214:217], v[98:101]
	v_mfma_f32_16x16x32_bf16 v[102:105], v[198:201], v[214:217], v[102:105]
	v_mfma_f32_16x16x32_bf16 v[82:85], v[190:193], v[222:225], v[82:85]
	v_mfma_f32_16x16x32_bf16 v[86:89], v[198:201], v[222:225], v[86:89]
	v_mfma_f32_16x16x32_bf16 v[66:69], v[190:193], v[230:233], v[66:69]
	v_mfma_f32_16x16x32_bf16 v[70:73], v[198:201], v[230:233], v[70:73]
	s_setprio 0
	s_barrier
; #define PG8_STAGE(bufoff, gbase, voff) do { _Pragma("unroll") for (int _i = 0; _i < 2; ++_i) \
;         __builtin_amdgcn_global_load_lds((const unsigned*)((const char*)(gbase) + (voff)[_i]), (LAS unsigned*)(lds + (bufoff) + ldsw + _i * 8192), 16, 0, 0); } while (0)
; #define PG8_LDA(dst, b, h) do { _Pragma("unroll") for (int m = 0; m < 4; ++m) _Pragma("unroll") for (int k = 0; k < 2; ++k) dst[m][k] = *(const LAS bf16x8*)(lds + PG8_SA(b, h) + aoff + m * 2048 + k * 1024); } while (0)
; #define PG8_MMA(ai, bj, At, Bt) do { __builtin_amdgcn_s_setprio(1); _Pragma("unroll") for (int m = 0; m < 4; ++m) _Pragma("unroll") for (int n = 0; n < 2; ++n) _Pragma("unroll") for (int k = 0; k < 2; ++k) \
;         acc[ai][bj][m][n] = __builtin_amdgcn_mfma_f32_16x16x32_bf16(Bt[n][k], At[m][k], acc[ai][bj][m][n], 0, 0, 0); __builtin_amdgcn_s_setprio(0); } while (0)
; #define PG8_WAIT_V(n) asm volatile("s_waitcnt vmcnt(" #n ")" ::: "memory")
; #define PG8_WAIT_L(n) asm volatile("s_waitcnt lgkmcnt(" #n ")" ::: "memory")
; #define PG8_BAR __builtin_amdgcn_s_barrier()
; #define PG8_SCHED __builtin_amdgcn_sched_barrier(0)
; template <class Epi>
; __device__ __forceinline__ void gemm_phase(LAS unsigned char* lds, const Gemm g, const Epi& E) {
;     ...
;             PG8_LDA(At, 1, 1); PG8_STAGE(PG8_SB(1, 0), b3, voffA); PG8_STAGE(PG8_SB(1, 1), b3 + hstep, voffA); PG8_STAGE(PG8_SA(1, 0), a3, voffA);
;             PG8_WAIT_V(8); PG8_WAIT_L(0); PG8_BAR; PG8_MMA(1, 0, At, B0); PG8_MMA(1, 1, At, B1); PG8_BAR; PG8_SCHED;
	s_add_i32 s10, s25, s26
	v_lshl_add_u64 v[164:165], v[164:165], 0, s[80:81]
	s_mov_b32 m0, s10
	ds_read_b128 v[202:205], v167 offset:49152
	ds_read_b128 v[206:209], v167 offset:50176
	ds_read_b128 v[210:213], v167 offset:51200
	ds_read_b128 v[214:217], v167 offset:52224
	ds_read_b128 v[218:221], v167 offset:53248
	ds_read_b128 v[222:225], v167 offset:54272
	ds_read_b128 v[226:229], v167 offset:55296
	ds_read_b128 v[230:233], v167 offset:56320
	global_load_lds_dwordx4 v[164:165], off
	s_add_i32 m0, s10, 0x2000
	s_add_u32 s4, s4, 0x40080
	v_lshl_add_u64 v[164:165], v[168:169], 0, s[80:81]
	s_addc_u32 s5, s5, 0
	s_add_i32 s10, s79, s26
	global_load_lds_dwordx4 v[164:165], off
	v_lshl_add_u64 v[164:165], s[4:5], 0, v[0:1]
	s_mov_b32 m0, s10
	s_nop 0
	global_load_lds_dwordx4 v[164:165], off
	v_lshl_add_u64 v[164:165], s[4:5], 0, v[146:147]
	s_add_i32 m0, s10, 0x2000
	s_nop 0
	global_load_lds_dwordx4 v[164:165], off
	v_lshl_add_u64 v[164:165], v[234:235], 0, s[80:81]
	s_mov_b32 m0, s37
	s_nop 0
	global_load_lds_dwordx4 v[164:165], off
	v_lshl_add_u64 v[164:165], v[236:237], 0, s[80:81]
	s_mov_b32 m0, s93
	s_nop 0
	global_load_lds_dwordx4 v[164:165], off
	s_waitcnt vmcnt(8)
	s_waitcnt lgkmcnt(0)
	s_barrier
	s_setprio 1
	s_waitcnt lgkmcnt(0)
	v_mfma_f32_16x16x32_bf16 v[58:61], v[130:133], v[202:205], v[58:61]
	v_mfma_f32_16x16x32_bf16 v[62:65], v[152:155], v[202:205], v[62:65]
	v_mfma_f32_16x16x32_bf16 v[42:45], v[130:133], v[210:213], v[42:45]
	v_mfma_f32_16x16x32_bf16 v[46:49], v[152:155], v[210:213], v[46:49]
	v_mfma_f32_16x16x32_bf16 v[26:29], v[130:133], v[218:221], v[26:29]
	v_mfma_f32_16x16x32_bf16 v[30:33], v[152:155], v[218:221], v[30:33]
	v_mfma_f32_16x16x32_bf16 v[10:13], v[130:133], v[226:229], v[10:13]
	v_mfma_f32_16x16x32_bf16 v[14:17], v[152:155], v[226:229], v[14:17]
	v_mfma_f32_16x16x32_bf16 v[58:61], v[134:137], v[206:209], v[58:61]
	v_mfma_f32_16x16x32_bf16 v[62:65], v[156:159], v[206:209], v[62:65]
	v_mfma_f32_16x16x32_bf16 v[42:45], v[134:137], v[214:217], v[42:45]
	v_mfma_f32_16x16x32_bf16 v[46:49], v[156:159], v[214:217], v[46:49]
	v_mfma_f32_16x16x32_bf16 v[26:29], v[134:137], v[222:225], v[26:29]
	v_mfma_f32_16x16x32_bf16 v[30:33], v[156:159], v[222:225], v[30:33]
	v_mfma_f32_16x16x32_bf16 v[10:13], v[134:137], v[230:233], v[10:13]
	v_mfma_f32_16x16x32_bf16 v[14:17], v[156:159], v[230:233], v[14:17]
	v_mfma_f32_16x16x32_bf16 v[50:53], v[160:163], v[202:205], v[50:53]
	v_mfma_f32_16x16x32_bf16 v[54:57], v[194:197], v[202:205], v[54:57]
	v_mfma_f32_16x16x32_bf16 v[34:37], v[160:163], v[210:213], v[34:37]
	v_mfma_f32_16x16x32_bf16 v[38:41], v[194:197], v[210:213], v[38:41]
	v_mfma_f32_16x16x32_bf16 v[18:21], v[160:163], v[218:221], v[18:21]
	v_mfma_f32_16x16x32_bf16 v[22:25], v[194:197], v[218:221], v[22:25]
	v_mfma_f32_16x16x32_bf16 v[6:9], v[160:163], v[226:229], v[6:9]
	v_mfma_f32_16x16x32_bf16 v[2:5], v[194:197], v[226:229], v[2:5]
	v_mfma_f32_16x16x32_bf16 v[50:53], v[190:193], v[206:209], v[50:53]
	v_mfma_f32_16x16x32_bf16 v[54:57], v[198:201], v[206:209], v[54:57]
	v_mfma_f32_16x16x32_bf16 v[34:37], v[190:193], v[214:217], v[34:37]
	v_mfma_f32_16x16x32_bf16 v[38:41], v[198:201], v[214:217], v[38:41]
	v_mfma_f32_16x16x32_bf16 v[18:21], v[190:193], v[222:225], v[18:21]
	v_mfma_f32_16x16x32_bf16 v[22:25], v[198:201], v[222:225], v[22:25]
	v_mfma_f32_16x16x32_bf16 v[6:9], v[190:193], v[230:233], v[6:9]
	v_mfma_f32_16x16x32_bf16 v[2:5], v[198:201], v[230:233], v[2:5]
	s_setprio 0
	s_barrier
	s_add_u32 s8, s8, 0x100
	s_addc_u32 s9, s9, 0
	s_add_u32 s71, s71, 0x100
	s_addc_u32 s75, s75, 0
	s_cmp_ge_i32 s78, s72
	s_mov_b32 s4, s78
	s_cbranch_scc0 .LBB0_95
	s_branch .Lk1_exit

; #define PG8_STAGE(bufoff, gbase, voff) do { _Pragma("unroll") for (int _i = 0; _i < 2; ++_i) \
;         __builtin_amdgcn_global_load_lds((const unsigned*)((const char*)(gbase) + (voff)[_i]), (LAS unsigned*)(lds + (bufoff) + ldsw + _i * 8192), 16, 0, 0); } while (0)
; #define PG8_LDA(dst, b, h) do { _Pragma("unroll") for (int m = 0; m < 4; ++m) _Pragma("unroll") for (int k = 0; k < 2; ++k) dst[m][k] = *(const LAS bf16x8*)(lds + PG8_SA(b, h) + aoff + m * 2048 + k * 1024); } while (0)
; #define PG8_LDB(dst, b, h) do { _Pragma("unroll") for (int n = 0; n < 2; ++n) _Pragma("unroll") for (int k = 0; k < 2; ++k) dst[n][k] = *(const LAS bf16x8*)(lds + PG8_SB(b, h) + boff + n * 2048 + k * 1024); } while (0)
; #define PG8_MMA(ai, bj, At, Bt) do { __builtin_amdgcn_s_setprio(1); _Pragma("unroll") for (int m = 0; m < 4; ++m) _Pragma("unroll") for (int n = 0; n < 2; ++n) _Pragma("unroll") for (int k = 0; k < 2; ++k) \
;         acc[ai][bj][m][n] = __builtin_amdgcn_mfma_f32_16x16x32_bf16(Bt[n][k], At[m][k], acc[ai][bj][m][n], 0, 0, 0); __builtin_amdgcn_s_setprio(0); } while (0)
; #define PG8_WAIT_V(n) asm volatile("s_waitcnt vmcnt(" #n ")" ::: "memory")
; #define PG8_WAIT_L(n) asm volatile("s_waitcnt lgkmcnt(" #n ")" ::: "memory")
; #define PG8_BAR __builtin_amdgcn_s_barrier()
; #define PG8_SCHED __builtin_amdgcn_sched_barrier(0)
; template <class Epi>
; __device__ __forceinline__ void gemm_phase(LAS unsigned char* lds, const Gemm g, const Epi& E) {
;     ...
;             const bool last = (t == nt - 2);
;             const char* a1 = cA + (size_t)(t + 1) * kstep;
;             const char* a2 = last ? nA : cA + (size_t)(t + 2) * kstep; const char* b2 = last ? nB : cB + (size_t)(t + 2) * kstep;
;             const char* a3 = a2 + kstep; const char* b3 = b2 + kstep;
;             PG8_LDB(B0, 0, 0); PG8_LDB(B1, 0, 1); PG8_SCHED; PG8_LDA(At, 0, 0); PG8_STAGE(PG8_SA(1, 1), a1 + hstep, voffA);
;             PG8_WAIT_V(8); PG8_WAIT_L(0); PG8_BAR; PG8_MMA(0, 0, At, B0); PG8_MMA(0, 1, At, B1); PG8_BAR; PG8_SCHED;
;             PG8_LDA(At, 0, 1); PG8_STAGE(PG8_SB(0, 0), b2, voffA); PG8_STAGE(PG8_SB(0, 1), b2 + hstep, voffA); PG8_STAGE(PG8_SA(0, 0), a2, voffA);
;             PG8_WAIT_V(8); PG8_WAIT_L(0); PG8_BAR; PG8_MMA(1, 0, At, B0); PG8_MMA(1, 1, At, B1); PG8_BAR; PG8_SCHED;
.LBB0_95:
	s_add_i32 s78, s4, 2
	s_add_u32 s5, s8, 0xfffc0080
	s_addc_u32 s10, s9, -1
	s_cmp_eq_u32 s69, s4
	s_cselect_b32 s11, s2, s10
	s_cselect_b32 s10, s12, s5
	s_cselect_b32 s5, s13, s75
	s_cselect_b32 s4, s15, s71
	s_add_i32 s25, 0, 0x14000
	v_add_u32_e32 v156, s21, v166
	v_add_u32_e32 v164, s25, v166
	ds_read_b128 v[130:133], v156
	ds_read_b128 v[134:137], v156 offset:1024
	ds_read_b128 v[152:155], v156 offset:2048
	ds_read_b128 v[156:159], v156 offset:3072
	ds_read_b128 v[160:163], v164
	ds_read_b128 v[190:193], v164 offset:1024
	ds_read_b128 v[194:197], v164 offset:2048
	ds_read_b128 v[198:201], v164 offset:3072
	v_lshl_add_u64 v[164:165], s[8:9], 0, v[148:149]
	s_add_i32 m0, s53, 0xc000
	ds_read_b128 v[202:205], v167
	ds_read_b128 v[206:209], v167 offset:1024
	ds_read_b128 v[210:213], v167 offset:2048
	ds_read_b128 v[214:217], v167 offset:3072
	ds_read_b128 v[218:221], v167 offset:4096
	ds_read_b128 v[222:225], v167 offset:5120
	ds_read_b128 v[226:229], v167 offset:6144
	ds_read_b128 v[230:233], v167 offset:7168
	global_load_lds_dwordx4 v[164:165], off
	v_lshl_add_u64 v[164:165], s[8:9], 0, v[150:151]
	s_add_i32 m0, s53, 0xe000
	s_nop 0
	global_load_lds_dwordx4 v[164:165], off
	s_waitcnt vmcnt(8)
	s_waitcnt lgkmcnt(0)
	s_barrier
	s_setprio 1
	s_waitcnt lgkmcnt(0)
	v_mfma_f32_16x16x32_bf16 v[122:125], v[130:133], v[202:205], v[122:125]
	v_mfma_f32_16x16x32_bf16 v[126:129], v[152:155], v[202:205], v[126:129]
	v_mfma_f32_16x16x32_bf16 v[106:109], v[130:133], v[210:213], v[106:109]
	v_mfma_f32_16x16x32_bf16 v[110:113], v[152:155], v[210:213], v[110:113]
	v_mfma_f32_16x16x32_bf16 v[90:93], v[130:133], v[218:221], v[90:93]
	v_mfma_f32_16x16x32_bf16 v[94:97], v[152:155], v[218:221], v[94:97]
	v_mfma_f32_16x16x32_bf16 v[74:77], v[130:133], v[226:229], v[74:77]
	v_mfma_f32_16x16x32_bf16 v[78:81], v[152:155], v[226:229], v[78:81]
	v_mfma_f32_16x16x32_bf16 v[122:125], v[134:137], v[206:209], v[122:125]
	v_mfma_f32_16x16x32_bf16 v[126:129], v[156:159], v[206:209], v[126:129]
	v_mfma_f32_16x16x32_bf16 v[106:109], v[134:137], v[214:217], v[106:109]
	v_mfma_f32_16x16x32_bf16 v[110:113], v[156:159], v[214:217], v[110:113]
	v_mfma_f32_16x16x32_bf16 v[90:93], v[134:137], v[222:225], v[90:93]
	v_mfma_f32_16x16x32_bf16 v[94:97], v[156:159], v[222:225], v[94:97]
	v_mfma_f32_16x16x32_bf16 v[74:77], v[134:137], v[230:233], v[74:77]
	v_mfma_f32_16x16x32_bf16 v[78:81], v[156:159], v[230:233], v[78:81]
	v_mfma_f32_16x16x32_bf16 v[114:117], v[160:163], v[202:205], v[114:117]
	v_mfma_f32_16x16x32_bf16 v[118:121], v[194:197], v[202:205], v[118:121]
	v_mfma_f32_16x16x32_bf16 v[98:101], v[160:163], v[210:213], v[98:101]
	v_mfma_f32_16x16x32_bf16 v[102:105], v[194:197], v[210:213], v[102:105]
	v_mfma_f32_16x16x32_bf16 v[82:85], v[160:163], v[218:221], v[82:85]
	v_mfma_f32_16x16x32_bf16 v[86:89], v[194:197], v[218:221], v[86:89]
	v_mfma_f32_16x16x32_bf16 v[66:69], v[160:163], v[226:229], v[66:69]
	v_mfma_f32_16x16x32_bf16 v[70:73], v[194:197], v[226:229], v[70:73]
	v_mfma_f32_16x16x32_bf16 v[114:117], v[190:193], v[206:209], v[114:117]
	v_mfma_f32_16x16x32_bf16 v[118:121], v[198:201], v[206:209], v[118:121]
	v_mfma_f32_16x16x32_bf16 v[98:101], v[190:193], v[214:217], v[98:101]
	v_mfma_f32_16x16x32_bf16 v[102:105], v[198:201], v[214:217], v[102:105]
	v_mfma_f32_16x16x32_bf16 v[82:85], v[190:193], v[222:225], v[82:85]
	v_mfma_f32_16x16x32_bf16 v[86:89], v[198:201], v[222:225], v[86:89]
	v_mfma_f32_16x16x32_bf16 v[66:69], v[190:193], v[230:233], v[66:69]
	v_mfma_f32_16x16x32_bf16 v[70:73], v[198:201], v[230:233], v[70:73]
	s_setprio 0
	s_barrier
	s_add_i32 s79, s21, s26
	v_lshl_add_u64 v[164:165], s[4:5], 0, v[0:1]
	s_mov_b32 m0, s79
	ds_read_b128 v[202:205], v167 offset:16384
	ds_read_b128 v[206:209], v167 offset:17408
	ds_read_b128 v[210:213], v167 offset:18432
	ds_read_b128 v[214:217], v167 offset:19456
	ds_read_b128 v[218:221], v167 offset:20480
	ds_read_b128 v[222:225], v167 offset:21504
	ds_read_b128 v[226:229], v167 offset:22528
	ds_read_b128 v[230:233], v167 offset:23552
	global_load_lds_dwordx4 v[164:165], off
	s_add_i32 m0, s79, 0x2000
	s_add_u32 vcc_lo, s4, 0x40000
	v_lshl_add_u64 v[168:169], s[4:5], 0, v[146:147]
	s_addc_u32 vcc_hi, s5, 0
	s_add_i32 s25, s25, s26
	global_load_lds_dwordx4 v[168:169], off
	v_lshl_add_u64 v[234:235], vcc, 0, v[0:1]
	s_mov_b32 m0, s25
	v_lshl_add_u64 v[236:237], s[10:11], 0, v[146:147]
	global_load_lds_dwordx4 v[234:235], off
	v_lshl_add_u64 v[234:235], vcc, 0, v[146:147]
	s_add_i32 m0, s25, 0x2000
	s_nop 0
	global_load_lds_dwordx4 v[234:235], off
	v_lshl_add_u64 v[234:235], s[10:11], 0, v[0:1]
	s_mov_b32 m0, s53
	s_nop 0
	global_load_lds_dwordx4 v[234:235], off
	s_mov_b32 m0, s73
	s_nop 0
	global_load_lds_dwordx4 v[236:237], off
	s_waitcnt vmcnt(8)
	s_waitcnt lgkmcnt(0)
	s_barrier
; #define PG8_STAGE(bufoff, gbase, voff) do { _Pragma("unroll") for (int _i = 0; _i < 2; ++_i) \
;         __builtin_amdgcn_global_load_lds((const unsigned*)((const char*)(gbase) + (voff)[_i]), (LAS unsigned*)(lds + (bufoff) + ldsw + _i * 8192), 16, 0, 0); } while (0)
; #define PG8_LDA(dst, b, h) do { _Pragma("unroll") for (int m = 0; m < 4; ++m) _Pragma("unroll") for (int k = 0; k < 2; ++k) dst[m][k] = *(const LAS bf16x8*)(lds + PG8_SA(b, h) + aoff + m * 2048 + k * 1024); } while (0)
; #define PG8_LDB(dst, b, h) do { _Pragma("unroll") for (int n = 0; n < 2; ++n) _Pragma("unroll") for (int k = 0; k < 2; ++k) dst[n][k] = *(const LAS bf16x8*)(lds + PG8_SB(b, h) + boff + n * 2048 + k * 1024); } while (0)
; #define PG8_MMA(ai, bj, At, Bt) do { __builtin_amdgcn_s_setprio(1); _Pragma("unroll") for (int m = 0; m < 4; ++m) _Pragma("unroll") for (int n = 0; n < 2; ++n) _Pragma("unroll") for (int k = 0; k < 2; ++k) \
;         acc[ai][bj][m][n] = __builtin_amdgcn_mfma_f32_16x16x32_bf16(Bt[n][k], At[m][k], acc[ai][bj][m][n], 0, 0, 0); __builtin_amdgcn_s_setprio(0); } while (0)
; #define PG8_WAIT_V(n) asm volatile("s_waitcnt vmcnt(" #n ")" ::: "memory")
; #define PG8_WAIT_L(n) asm volatile("s_waitcnt lgkmcnt(" #n ")" ::: "memory")
; #define PG8_BAR __builtin_amdgcn_s_barrier()
; #define PG8_SCHED __builtin_amdgcn_sched_barrier(0)
; template <class Epi>
; __device__ __forceinline__ void gemm_phase(LAS unsigned char* lds, const Gemm g, const Epi& E) {
;     ...
;             PG8_WAIT_V(8); PG8_WAIT_L(0); PG8_BAR; PG8_MMA(1, 0, At, B0); PG8_MMA(1, 1, At, B1); PG8_BAR; PG8_SCHED;
;             PG8_LDB(B0, 1, 0); PG8_LDB(B1, 1, 1); PG8_SCHED; PG8_LDA(At, 1, 0); PG8_STAGE(PG8_SA(0, 1), a2 + hstep, voffA);
;             PG8_WAIT_V(8); PG8_WAIT_L(0); PG8_BAR; PG8_MMA(0, 0, At, B0); PG8_MMA(0, 1, At, B1); PG8_BAR; PG8_SCHED;
	s_setprio 1
	s_waitcnt lgkmcnt(0)
	v_mfma_f32_16x16x32_bf16 v[58:61], v[130:133], v[202:205], v[58:61]
	v_mfma_f32_16x16x32_bf16 v[62:65], v[152:155], v[202:205], v[62:65]
	v_mfma_f32_16x16x32_bf16 v[42:45], v[130:133], v[210:213], v[42:45]
	v_mfma_f32_16x16x32_bf16 v[46:49], v[152:155], v[210:213], v[46:49]
	v_mfma_f32_16x16x32_bf16 v[26:29], v[130:133], v[218:221], v[26:29]
	v_mfma_f32_16x16x32_bf16 v[30:33], v[152:155], v[218:221], v[30:33]
	v_mfma_f32_16x16x32_bf16 v[10:13], v[130:133], v[226:229], v[10:13]
	v_mfma_f32_16x16x32_bf16 v[14:17], v[152:155], v[226:229], v[14:17]
	v_mfma_f32_16x16x32_bf16 v[58:61], v[134:137], v[206:209], v[58:61]
	v_mfma_f32_16x16x32_bf16 v[62:65], v[156:159], v[206:209], v[62:65]
	v_mfma_f32_16x16x32_bf16 v[42:45], v[134:137], v[214:217], v[42:45]
	v_mfma_f32_16x16x32_bf16 v[46:49], v[156:159], v[214:217], v[46:49]
	v_mfma_f32_16x16x32_bf16 v[26:29], v[134:137], v[222:225], v[26:29]
	v_mfma_f32_16x16x32_bf16 v[30:33], v[156:159], v[222:225], v[30:33]
	v_mfma_f32_16x16x32_bf16 v[10:13], v[134:137], v[230:233], v[10:13]
	v_mfma_f32_16x16x32_bf16 v[14:17], v[156:159], v[230:233], v[14:17]
	v_mfma_f32_16x16x32_bf16 v[50:53], v[160:163], v[202:205], v[50:53]
	v_mfma_f32_16x16x32_bf16 v[54:57], v[194:197], v[202:205], v[54:57]
	v_mfma_f32_16x16x32_bf16 v[34:37], v[160:163], v[210:213], v[34:37]
	v_mfma_f32_16x16x32_bf16 v[38:41], v[194:197], v[210:213], v[38:41]
	v_mfma_f32_16x16x32_bf16 v[18:21], v[160:163], v[218:221], v[18:21]
	v_mfma_f32_16x16x32_bf16 v[22:25], v[194:197], v[218:221], v[22:25]
	v_mfma_f32_16x16x32_bf16 v[6:9], v[160:163], v[226:229], v[6:9]
	v_mfma_f32_16x16x32_bf16 v[2:5], v[194:197], v[226:229], v[2:5]
	v_mfma_f32_16x16x32_bf16 v[50:53], v[190:193], v[206:209], v[50:53]
	v_mfma_f32_16x16x32_bf16 v[54:57], v[198:201], v[206:209], v[54:57]
	v_mfma_f32_16x16x32_bf16 v[34:37], v[190:193], v[214:217], v[34:37]
	v_mfma_f32_16x16x32_bf16 v[38:41], v[198:201], v[214:217], v[38:41]
	v_mfma_f32_16x16x32_bf16 v[18:21], v[190:193], v[222:225], v[18:21]
	v_mfma_f32_16x16x32_bf16 v[22:25], v[198:201], v[222:225], v[22:25]
	v_mfma_f32_16x16x32_bf16 v[6:9], v[190:193], v[230:233], v[6:9]
	v_mfma_f32_16x16x32_bf16 v[2:5], v[198:201], v[230:233], v[2:5]
	s_setprio 0
	s_barrier
	s_add_i32 s25, 0, 0x18000
	s_add_i32 s79, 0, 0x1c000
	v_add_u32_e32 v156, s25, v166
	v_add_u32_e32 v189, s79, v166
	ds_read_b128 v[130:133], v156
	ds_read_b128 v[134:137], v156 offset:1024
	ds_read_b128 v[152:155], v156 offset:2048
	ds_read_b128 v[156:159], v156 offset:3072
	ds_read_b128 v[160:163], v189
	ds_read_b128 v[190:193], v189 offset:1024
	ds_read_b128 v[194:197], v189 offset:2048
	ds_read_b128 v[198:201], v189 offset:3072
	s_add_u32 s10, s10, 0x40000
	s_addc_u32 s11, s11, 0
	s_mov_b32 m0, s76
	v_lshl_add_u64 v[238:239], s[10:11], 0, v[0:1]
	ds_read_b128 v[202:205], v167 offset:32768
	ds_read_b128 v[206:209], v167 offset:33792
	ds_read_b128 v[210:213], v167 offset:34816
	ds_read_b128 v[214:217], v167 offset:35840
	ds_read_b128 v[218:221], v167 offset:36864
	ds_read_b128 v[222:225], v167 offset:37888
	ds_read_b128 v[226:229], v167 offset:38912
	ds_read_b128 v[230:233], v167 offset:39936
	global_load_lds_dwordx4 v[238:239], off
	v_lshl_add_u64 v[238:239], s[10:11], 0, v[146:147]
	s_mov_b32 m0, s77
	s_nop 0
	global_load_lds_dwordx4 v[238:239], off
	s_waitcnt vmcnt(8)
	s_waitcnt lgkmcnt(0)
	s_barrier
	s_setprio 1
	s_waitcnt lgkmcnt(0)
	v_mfma_f32_16x16x32_bf16 v[122:125], v[130:133], v[202:205], v[122:125]
	v_mfma_f32_16x16x32_bf16 v[126:129], v[152:155], v[202:205], v[126:129]
	v_mfma_f32_16x16x32_bf16 v[106:109], v[130:133], v[210:213], v[106:109]
	v_mfma_f32_16x16x32_bf16 v[110:113], v[152:155], v[210:213], v[110:113]
	v_mfma_f32_16x16x32_bf16 v[90:93], v[130:133], v[218:221], v[90:93]
	v_mfma_f32_16x16x32_bf16 v[94:97], v[152:155], v[218:221], v[94:97]
	v_mfma_f32_16x16x32_bf16 v[74:77], v[130:133], v[226:229], v[74:77]
	v_mfma_f32_16x16x32_bf16 v[78:81], v[152:155], v[226:229], v[78:81]
	v_mfma_f32_16x16x32_bf16 v[122:125], v[134:137], v[206:209], v[122:125]
	v_mfma_f32_16x16x32_bf16 v[126:129], v[156:159], v[206:209], v[126:129]
	v_mfma_f32_16x16x32_bf16 v[106:109], v[134:137], v[214:217], v[106:109]
	v_mfma_f32_16x16x32_bf16 v[110:113], v[156:159], v[214:217], v[110:113]
	v_mfma_f32_16x16x32_bf16 v[90:93], v[134:137], v[222:225], v[90:93]
	v_mfma_f32_16x16x32_bf16 v[94:97], v[156:159], v[222:225], v[94:97]
	v_mfma_f32_16x16x32_bf16 v[74:77], v[134:137], v[230:233], v[74:77]
	v_mfma_f32_16x16x32_bf16 v[78:81], v[156:159], v[230:233], v[78:81]
	v_mfma_f32_16x16x32_bf16 v[114:117], v[160:163], v[202:205], v[114:117]
	v_mfma_f32_16x16x32_bf16 v[118:121], v[194:197], v[202:205], v[118:121]
	v_mfma_f32_16x16x32_bf16 v[98:101], v[160:163], v[210:213], v[98:101]
	v_mfma_f32_16x16x32_bf16 v[102:105], v[194:197], v[210:213], v[102:105]
	v_mfma_f32_16x16x32_bf16 v[82:85], v[160:163], v[218:221], v[82:85]
	v_mfma_f32_16x16x32_bf16 v[86:89], v[194:197], v[218:221], v[86:89]
	v_mfma_f32_16x16x32_bf16 v[66:69], v[160:163], v[226:229], v[66:69]
	v_mfma_f32_16x16x32_bf16 v[70:73], v[194:197], v[226:229], v[70:73]
	v_mfma_f32_16x16x32_bf16 v[114:117], v[190:193], v[206:209], v[114:117]
	v_mfma_f32_16x16x32_bf16 v[118:121], v[198:201], v[206:209], v[118:121]
	v_mfma_f32_16x16x32_bf16 v[98:101], v[190:193], v[214:217], v[98:101]
	v_mfma_f32_16x16x32_bf16 v[102:105], v[198:201], v[214:217], v[102:105]
	v_mfma_f32_16x16x32_bf16 v[82:85], v[190:193], v[222:225], v[82:85]
	v_mfma_f32_16x16x32_bf16 v[86:89], v[198:201], v[222:225], v[86:89]
	v_mfma_f32_16x16x32_bf16 v[66:69], v[190:193], v[230:233], v[66:69]
	v_mfma_f32_16x16x32_bf16 v[70:73], v[198:201], v[230:233], v[70:73]
	s_setprio 0
	s_barrier
; #define PG8_STAGE(bufoff, gbase, voff) do { _Pragma("unroll") for (int _i = 0; _i < 2; ++_i) \
;         __builtin_amdgcn_global_load_lds((const unsigned*)((const char*)(gbase) + (voff)[_i]), (LAS unsigned*)(lds + (bufoff) + ldsw + _i * 8192), 16, 0, 0); } while (0)
; #define PG8_LDA(dst, b, h) do { _Pragma("unroll") for (int m = 0; m < 4; ++m) _Pragma("unroll") for (int k = 0; k < 2; ++k) dst[m][k] = *(const LAS bf16x8*)(lds + PG8_SA(b, h) + aoff + m * 2048 + k * 1024); } while (0)
; #define PG8_MMA(ai, bj, At, Bt) do { __builtin_amdgcn_s_setprio(1); _Pragma("unroll") for (int m = 0; m < 4; ++m) _Pragma("unroll") for (int n = 0; n < 2; ++n) _Pragma("unroll") for (int k = 0; k < 2; ++k) \
;         acc[ai][bj][m][n] = __builtin_amdgcn_mfma_f32_16x16x32_bf16(Bt[n][k], At[m][k], acc[ai][bj][m][n], 0, 0, 0); __builtin_amdgcn_s_setprio(0); } while (0)
; #define PG8_WAIT_V(n) asm volatile("s_waitcnt vmcnt(" #n ")" ::: "memory")
; #define PG8_WAIT_L(n) asm volatile("s_waitcnt lgkmcnt(" #n ")" ::: "memory")
; #define PG8_BAR __builtin_amdgcn_s_barrier()
; #define PG8_SCHED __builtin_amdgcn_sched_barrier(0)
; template <class Epi>
; __device__ __forceinline__ void gemm_phase(LAS unsigned char* lds, const Gemm g, const Epi& E) {
;     ...
;             PG8_LDA(At, 1, 1); PG8_STAGE(PG8_SB(1, 0), b3, voffA); PG8_STAGE(PG8_SB(1, 1), b3 + hstep, voffA); PG8_STAGE(PG8_SA(1, 0), a3, voffA);
;             PG8_WAIT_V(8); PG8_WAIT_L(0); PG8_BAR; PG8_MMA(1, 0, At, B0); PG8_MMA(1, 1, At, B1); PG8_BAR; PG8_SCHED;
	s_add_i32 s10, s25, s26
	v_lshl_add_u64 v[164:165], v[164:165], 0, s[80:81]
	s_mov_b32 m0, s10
	ds_read_b128 v[202:205], v167 offset:49152
	ds_read_b128 v[206:209], v167 offset:50176
	ds_read_b128 v[210:213], v167 offset:51200
	ds_read_b128 v[214:217], v167 offset:52224
	ds_read_b128 v[218:221], v167 offset:53248
	ds_read_b128 v[222:225], v167 offset:54272
	ds_read_b128 v[226:229], v167 offset:55296
	ds_read_b128 v[230:233], v167 offset:56320
	global_load_lds_dwordx4 v[164:165], off
	s_add_i32 m0, s10, 0x2000
	s_add_u32 s4, s4, 0x40080
	v_lshl_add_u64 v[164:165], v[168:169], 0, s[80:81]
	s_addc_u32 s5, s5, 0
	s_add_i32 s10, s79, s26
	global_load_lds_dwordx4 v[164:165], off
	v_lshl_add_u64 v[164:165], s[4:5], 0, v[0:1]
	s_mov_b32 m0, s10
	s_nop 0
	global_load_lds_dwordx4 v[164:165], off
	v_lshl_add_u64 v[164:165], s[4:5], 0, v[146:147]
	s_add_i32 m0, s10, 0x2000
	s_nop 0
	global_load_lds_dwordx4 v[164:165], off
	v_lshl_add_u64 v[164:165], v[234:235], 0, s[80:81]
	s_mov_b32 m0, s37
	s_nop 0
	global_load_lds_dwordx4 v[164:165], off
	v_lshl_add_u64 v[164:165], v[236:237], 0, s[80:81]
	s_mov_b32 m0, s93
	s_nop 0
	global_load_lds_dwordx4 v[164:165], off
	s_waitcnt vmcnt(8)
	s_waitcnt lgkmcnt(0)
	s_barrier
	s_setprio 1
	s_waitcnt lgkmcnt(0)
	v_mfma_f32_16x16x32_bf16 v[58:61], v[130:133], v[202:205], v[58:61]
	v_mfma_f32_16x16x32_bf16 v[62:65], v[152:155], v[202:205], v[62:65]
	v_mfma_f32_16x16x32_bf16 v[42:45], v[130:133], v[210:213], v[42:45]
	v_mfma_f32_16x16x32_bf16 v[46:49], v[152:155], v[210:213], v[46:49]
	v_mfma_f32_16x16x32_bf16 v[26:29], v[130:133], v[218:221], v[26:29]
	v_mfma_f32_16x16x32_bf16 v[30:33], v[152:155], v[218:221], v[30:33]
	v_mfma_f32_16x16x32_bf16 v[10:13], v[130:133], v[226:229], v[10:13]
	v_mfma_f32_16x16x32_bf16 v[14:17], v[152:155], v[226:229], v[14:17]
	v_mfma_f32_16x16x32_bf16 v[58:61], v[134:137], v[206:209], v[58:61]
	v_mfma_f32_16x16x32_bf16 v[62:65], v[156:159], v[206:209], v[62:65]
	v_mfma_f32_16x16x32_bf16 v[42:45], v[134:137], v[214:217], v[42:45]
	v_mfma_f32_16x16x32_bf16 v[46:49], v[156:159], v[214:217], v[46:49]
	v_mfma_f32_16x16x32_bf16 v[26:29], v[134:137], v[222:225], v[26:29]
	v_mfma_f32_16x16x32_bf16 v[30:33], v[156:159], v[222:225], v[30:33]
	v_mfma_f32_16x16x32_bf16 v[10:13], v[134:137], v[230:233], v[10:13]
	v_mfma_f32_16x16x32_bf16 v[14:17], v[156:159], v[230:233], v[14:17]
	v_mfma_f32_16x16x32_bf16 v[50:53], v[160:163], v[202:205], v[50:53]
	v_mfma_f32_16x16x32_bf16 v[54:57], v[194:197], v[202:205], v[54:57]
	v_mfma_f32_16x16x32_bf16 v[34:37], v[160:163], v[210:213], v[34:37]
	v_mfma_f32_16x16x32_bf16 v[38:41], v[194:197], v[210:213], v[38:41]
	v_mfma_f32_16x16x32_bf16 v[18:21], v[160:163], v[218:221], v[18:21]
	v_mfma_f32_16x16x32_bf16 v[22:25], v[194:197], v[218:221], v[22:25]
	v_mfma_f32_16x16x32_bf16 v[6:9], v[160:163], v[226:229], v[6:9]
	v_mfma_f32_16x16x32_bf16 v[2:5], v[194:197], v[226:229], v[2:5]
	v_mfma_f32_16x16x32_bf16 v[50:53], v[190:193], v[206:209], v[50:53]
	v_mfma_f32_16x16x32_bf16 v[54:57], v[198:201], v[206:209], v[54:57]
	v_mfma_f32_16x16x32_bf16 v[34:37], v[190:193], v[214:217], v[34:37]
	v_mfma_f32_16x16x32_bf16 v[38:41], v[198:201], v[214:217], v[38:41]
	v_mfma_f32_16x16x32_bf16 v[18:21], v[190:193], v[222:225], v[18:21]
	v_mfma_f32_16x16x32_bf16 v[22:25], v[198:201], v[222:225], v[22:25]
	v_mfma_f32_16x16x32_bf16 v[6:9], v[190:193], v[230:233], v[6:9]
	v_mfma_f32_16x16x32_bf16 v[2:5], v[198:201], v[230:233], v[2:5]
	s_setprio 0
	s_barrier
	s_add_u32 s8, s8, 0x100
	s_addc_u32 s9, s9, 0
	s_add_u32 s71, s71, 0x100
	s_addc_u32 s75, s75, 0
	s_cmp_ge_i32 s78, s72
	s_mov_b32 s4, s78
	s_cbranch_scc0 .LBB0_95

; #define PG8_STAGE(bufoff, gbase, voff) do { _Pragma("unroll") for (int _i = 0; _i < 2; ++_i) \
;         __builtin_amdgcn_global_load_lds((const unsigned*)((const char*)(gbase) + (voff)[_i]), (LAS unsigned*)(lds + (bufoff) + ldsw + _i * 8192), 16, 0, 0); } while (0)
; #define PG8_LDA(dst, b, h) do { _Pragma("unroll") for (int m = 0; m < 4; ++m) _Pragma("unroll") for (int k = 0; k < 2; ++k) dst[m][k] = *(const LAS bf16x8*)(lds + PG8_SA(b, h) + aoff + m * 2048 + k * 1024); } while (0)
; #define PG8_LDB(dst, b, h) do { _Pragma("unroll") for (int n = 0; n < 2; ++n) _Pragma("unroll") for (int k = 0; k < 2; ++k) dst[n][k] = *(const LAS bf16x8*)(lds + PG8_SB(b, h) + boff + n * 2048 + k * 1024); } while (0)
; #define PG8_MMA(ai, bj, At, Bt) do { __builtin_amdgcn_s_setprio(1); _Pragma("unroll") for (int m = 0; m < 4; ++m) _Pragma("unroll") for (int n = 0; n < 2; ++n) _Pragma("unroll") for (int k = 0; k < 2; ++k) \
;         acc[ai][bj][m][n] = __builtin_amdgcn_mfma_f32_16x16x32_bf16(Bt[n][k], At[m][k], acc[ai][bj][m][n], 0, 0, 0); __builtin_amdgcn_s_setprio(0); } while (0)
; #define PG8_WAIT_V(n) asm volatile("s_waitcnt vmcnt(" #n ")" ::: "memory")
; #define PG8_WAIT_L(n) asm volatile("s_waitcnt lgkmcnt(" #n ")" ::: "memory")
; #define PG8_BAR __builtin_amdgcn_s_barrier()
; #define PG8_SCHED __builtin_amdgcn_sched_barrier(0)
; template <class Epi>
; __device__ __forceinline__ void gemm_phase(LAS unsigned char* lds, const Gemm g, const Epi& E) {
;     ...
;             const bool last = (t == nt - 2);
;             const char* a1 = cA + (size_t)(t + 1) * kstep;
;             const char* a2 = last ? nA : cA + (size_t)(t + 2) * kstep; const char* b2 = last ? nB : cB + (size_t)(t + 2) * kstep;
;             const char* a3 = a2 + kstep; const char* b3 = b2 + kstep;
;             PG8_LDB(B0, 0, 0); PG8_LDB(B1, 0, 1); PG8_SCHED; PG8_LDA(At, 0, 0); PG8_STAGE(PG8_SA(1, 1), a1 + hstep, voffA);
;             PG8_WAIT_V(8); PG8_WAIT_L(0); PG8_BAR; PG8_MMA(0, 0, At, B0); PG8_MMA(0, 1, At, B1); PG8_BAR; PG8_SCHED;
;             PG8_LDA(At, 0, 1); PG8_STAGE(PG8_SB(0, 0), b2, voffA); PG8_STAGE(PG8_SB(0, 1), b2 + hstep, voffA); PG8_STAGE(PG8_SA(0, 0), a2, voffA);
;             PG8_WAIT_V(8); PG8_WAIT_L(0); PG8_BAR; PG8_MMA(1, 0, At, B0); PG8_MMA(1, 1, At, B1); PG8_BAR; PG8_SCHED;
.LBB0_407:
	s_add_i32 vcc_lo, s4, 2
	s_add_u32 s25, s62, 0x80
	s_addc_u32 s5, s63, 0
	s_cmp_eq_u32 s7, s4
	s_cselect_b32 s5, s55, s5
	s_cselect_b32 s4, s54, s25
	v_add_u32_e32 v133, s21, v189
	s_cselect_b32 s73, s57, s53
	s_cselect_b32 s72, s56, s15
	s_add_i32 s25, 0, 0x14000
	ds_read_b128 v[148:151], v133
	ds_read_b128 v[152:155], v133 offset:1024
	ds_read_b128 v[156:159], v133 offset:2048
	ds_read_b128 v[160:163], v133 offset:3072
	v_add_u32_e32 v133, s25, v189
	ds_read_b128 v[164:167], v133
	ds_read_b128 v[192:195], v133 offset:1024
	ds_read_b128 v[196:199], v133 offset:2048
	ds_read_b128 v[200:203], v133 offset:3072
	v_lshl_add_u64 v[168:169], s[62:63], 0, v[136:137]
	s_add_i32 m0, s71, 0xc000
	ds_read_b128 v[204:207], v190
	ds_read_b128 v[208:211], v190 offset:1024
	ds_read_b128 v[212:215], v190 offset:2048
	ds_read_b128 v[216:219], v190 offset:3072
	ds_read_b128 v[220:223], v190 offset:4096
	ds_read_b128 v[224:227], v190 offset:5120
	ds_read_b128 v[228:231], v190 offset:6144
	ds_read_b128 v[232:235], v190 offset:7168
	global_load_lds_dwordx4 v[168:169], off
	v_lshl_add_u64 v[168:169], s[62:63], 0, v[146:147]
	s_add_i32 m0, s71, 0xe000
	s_nop 0
	global_load_lds_dwordx4 v[168:169], off
	s_waitcnt vmcnt(8)
	s_waitcnt lgkmcnt(0)
	s_barrier
	s_setprio 1
	s_waitcnt lgkmcnt(0)
	v_mfma_f32_16x16x32_bf16 v[126:129], v[148:151], v[204:207], v[126:129]
	v_mfma_f32_16x16x32_bf16 v[122:125], v[156:159], v[204:207], v[122:125]
	v_mfma_f32_16x16x32_bf16 v[110:113], v[148:151], v[212:215], v[110:113]
	v_mfma_f32_16x16x32_bf16 v[106:109], v[156:159], v[212:215], v[106:109]
	v_mfma_f32_16x16x32_bf16 v[94:97], v[148:151], v[220:223], v[94:97]
	v_mfma_f32_16x16x32_bf16 v[90:93], v[156:159], v[220:223], v[90:93]
	v_mfma_f32_16x16x32_bf16 v[78:81], v[148:151], v[228:231], v[78:81]
	v_mfma_f32_16x16x32_bf16 v[74:77], v[156:159], v[228:231], v[74:77]
	v_mfma_f32_16x16x32_bf16 v[126:129], v[152:155], v[208:211], v[126:129]
	v_mfma_f32_16x16x32_bf16 v[122:125], v[160:163], v[208:211], v[122:125]
	v_mfma_f32_16x16x32_bf16 v[110:113], v[152:155], v[216:219], v[110:113]
	v_mfma_f32_16x16x32_bf16 v[106:109], v[160:163], v[216:219], v[106:109]
	v_mfma_f32_16x16x32_bf16 v[94:97], v[152:155], v[224:227], v[94:97]
	v_mfma_f32_16x16x32_bf16 v[90:93], v[160:163], v[224:227], v[90:93]
	v_mfma_f32_16x16x32_bf16 v[78:81], v[152:155], v[232:235], v[78:81]
	v_mfma_f32_16x16x32_bf16 v[74:77], v[160:163], v[232:235], v[74:77]
	v_mfma_f32_16x16x32_bf16 v[118:121], v[164:167], v[204:207], v[118:121]
	v_mfma_f32_16x16x32_bf16 v[114:117], v[196:199], v[204:207], v[114:117]
	v_mfma_f32_16x16x32_bf16 v[102:105], v[164:167], v[212:215], v[102:105]
	v_mfma_f32_16x16x32_bf16 v[98:101], v[196:199], v[212:215], v[98:101]
	v_mfma_f32_16x16x32_bf16 v[86:89], v[164:167], v[220:223], v[86:89]
	v_mfma_f32_16x16x32_bf16 v[82:85], v[196:199], v[220:223], v[82:85]
	v_mfma_f32_16x16x32_bf16 v[70:73], v[164:167], v[228:231], v[70:73]
	v_mfma_f32_16x16x32_bf16 v[66:69], v[196:199], v[228:231], v[66:69]
	v_mfma_f32_16x16x32_bf16 v[118:121], v[192:195], v[208:211], v[118:121]
	v_mfma_f32_16x16x32_bf16 v[114:117], v[200:203], v[208:211], v[114:117]
	v_mfma_f32_16x16x32_bf16 v[102:105], v[192:195], v[216:219], v[102:105]
	v_mfma_f32_16x16x32_bf16 v[98:101], v[200:203], v[216:219], v[98:101]
	v_mfma_f32_16x16x32_bf16 v[86:89], v[192:195], v[224:227], v[86:89]
	v_mfma_f32_16x16x32_bf16 v[82:85], v[200:203], v[224:227], v[82:85]
	v_mfma_f32_16x16x32_bf16 v[70:73], v[192:195], v[232:235], v[70:73]
	v_mfma_f32_16x16x32_bf16 v[66:69], v[200:203], v[232:235], v[66:69]
	s_setprio 0
	s_barrier
	s_add_i32 vcc_hi, s21, s37
	v_lshl_add_u64 v[168:169], s[72:73], 0, v[0:1]
	s_mov_b32 m0, vcc_hi
	ds_read_b128 v[204:207], v190 offset:16384
	ds_read_b128 v[208:211], v190 offset:17408
	ds_read_b128 v[212:215], v190 offset:18432
	ds_read_b128 v[216:219], v190 offset:19456
	ds_read_b128 v[220:223], v190 offset:20480
	ds_read_b128 v[224:227], v190 offset:21504
	ds_read_b128 v[228:231], v190 offset:22528
	ds_read_b128 v[232:235], v190 offset:23552
	global_load_lds_dwordx4 v[168:169], off
	s_add_i32 m0, vcc_hi, 0x2000
	v_lshl_add_u64 v[236:237], s[72:73], 0, v[130:131]
	s_add_u32 s72, s72, s82
	s_addc_u32 s73, s73, 0
	s_add_i32 s25, s25, s37
	global_load_lds_dwordx4 v[236:237], off
	v_lshl_add_u64 v[238:239], s[72:73], 0, v[0:1]
	s_mov_b32 m0, s25
	v_lshl_add_u64 v[240:241], s[72:73], 0, v[130:131]
	global_load_lds_dwordx4 v[238:239], off
	s_add_i32 m0, s25, 0x2000
	v_lshl_add_u64 v[242:243], s[4:5], 0, v[0:1]
	global_load_lds_dwordx4 v[240:241], off
	s_mov_b32 m0, s71
	v_lshl_add_u64 v[244:245], s[4:5], 0, v[130:131]
	global_load_lds_dwordx4 v[242:243], off
	s_mov_b32 m0, s75
	s_nop 0
	global_load_lds_dwordx4 v[244:245], off
	s_waitcnt vmcnt(8)
	s_waitcnt lgkmcnt(0)
	s_barrier
; #define PG8_STAGE(bufoff, gbase, voff) do { _Pragma("unroll") for (int _i = 0; _i < 2; ++_i) \
;         __builtin_amdgcn_global_load_lds((const unsigned*)((const char*)(gbase) + (voff)[_i]), (LAS unsigned*)(lds + (bufoff) + ldsw + _i * 8192), 16, 0, 0); } while (0)
; #define PG8_LDA(dst, b, h) do { _Pragma("unroll") for (int m = 0; m < 4; ++m) _Pragma("unroll") for (int k = 0; k < 2; ++k) dst[m][k] = *(const LAS bf16x8*)(lds + PG8_SA(b, h) + aoff + m * 2048 + k * 1024); } while (0)
; #define PG8_LDB(dst, b, h) do { _Pragma("unroll") for (int n = 0; n < 2; ++n) _Pragma("unroll") for (int k = 0; k < 2; ++k) dst[n][k] = *(const LAS bf16x8*)(lds + PG8_SB(b, h) + boff + n * 2048 + k * 1024); } while (0)
; #define PG8_MMA(ai, bj, At, Bt) do { __builtin_amdgcn_s_setprio(1); _Pragma("unroll") for (int m = 0; m < 4; ++m) _Pragma("unroll") for (int n = 0; n < 2; ++n) _Pragma("unroll") for (int k = 0; k < 2; ++k) \
;         acc[ai][bj][m][n] = __builtin_amdgcn_mfma_f32_16x16x32_bf16(Bt[n][k], At[m][k], acc[ai][bj][m][n], 0, 0, 0); __builtin_amdgcn_s_setprio(0); } while (0)
; #define PG8_WAIT_V(n) asm volatile("s_waitcnt vmcnt(" #n ")" ::: "memory")
; #define PG8_WAIT_L(n) asm volatile("s_waitcnt lgkmcnt(" #n ")" ::: "memory")
; #define PG8_BAR __builtin_amdgcn_s_barrier()
; #define PG8_SCHED __builtin_amdgcn_sched_barrier(0)
; template <class Epi>
; __device__ __forceinline__ void gemm_phase(LAS unsigned char* lds, const Gemm g, const Epi& E) {
;     ...
;             PG8_WAIT_V(8); PG8_WAIT_L(0); PG8_BAR; PG8_MMA(1, 0, At, B0); PG8_MMA(1, 1, At, B1); PG8_BAR; PG8_SCHED;
;             PG8_LDB(B0, 1, 0); PG8_LDB(B1, 1, 1); PG8_SCHED; PG8_LDA(At, 1, 0); PG8_STAGE(PG8_SA(0, 1), a2 + hstep, voffA);
;             PG8_WAIT_V(8); PG8_WAIT_L(0); PG8_BAR; PG8_MMA(0, 0, At, B0); PG8_MMA(0, 1, At, B1); PG8_BAR; PG8_SCHED;
	s_setprio 1
	s_waitcnt lgkmcnt(0)
	v_mfma_f32_16x16x32_bf16 v[62:65], v[148:151], v[204:207], v[62:65]
	v_mfma_f32_16x16x32_bf16 v[58:61], v[156:159], v[204:207], v[58:61]
	v_mfma_f32_16x16x32_bf16 v[46:49], v[148:151], v[212:215], v[46:49]
	v_mfma_f32_16x16x32_bf16 v[42:45], v[156:159], v[212:215], v[42:45]
	v_mfma_f32_16x16x32_bf16 v[30:33], v[148:151], v[220:223], v[30:33]
	v_mfma_f32_16x16x32_bf16 v[26:29], v[156:159], v[220:223], v[26:29]
	v_mfma_f32_16x16x32_bf16 v[14:17], v[148:151], v[228:231], v[14:17]
	v_mfma_f32_16x16x32_bf16 v[10:13], v[156:159], v[228:231], v[10:13]
	v_mfma_f32_16x16x32_bf16 v[62:65], v[152:155], v[208:211], v[62:65]
	v_mfma_f32_16x16x32_bf16 v[58:61], v[160:163], v[208:211], v[58:61]
	v_mfma_f32_16x16x32_bf16 v[46:49], v[152:155], v[216:219], v[46:49]
	v_mfma_f32_16x16x32_bf16 v[42:45], v[160:163], v[216:219], v[42:45]
	v_mfma_f32_16x16x32_bf16 v[30:33], v[152:155], v[224:227], v[30:33]
	v_mfma_f32_16x16x32_bf16 v[26:29], v[160:163], v[224:227], v[26:29]
	v_mfma_f32_16x16x32_bf16 v[14:17], v[152:155], v[232:235], v[14:17]
	v_mfma_f32_16x16x32_bf16 v[10:13], v[160:163], v[232:235], v[10:13]
	v_mfma_f32_16x16x32_bf16 v[54:57], v[164:167], v[204:207], v[54:57]
	v_mfma_f32_16x16x32_bf16 v[50:53], v[196:199], v[204:207], v[50:53]
	v_mfma_f32_16x16x32_bf16 v[38:41], v[164:167], v[212:215], v[38:41]
	v_mfma_f32_16x16x32_bf16 v[34:37], v[196:199], v[212:215], v[34:37]
	v_mfma_f32_16x16x32_bf16 v[22:25], v[164:167], v[220:223], v[22:25]
	v_mfma_f32_16x16x32_bf16 v[18:21], v[196:199], v[220:223], v[18:21]
	v_mfma_f32_16x16x32_bf16 v[6:9], v[164:167], v[228:231], v[6:9]
	v_mfma_f32_16x16x32_bf16 v[2:5], v[196:199], v[228:231], v[2:5]
	v_mfma_f32_16x16x32_bf16 v[54:57], v[192:195], v[208:211], v[54:57]
	v_mfma_f32_16x16x32_bf16 v[50:53], v[200:203], v[208:211], v[50:53]
	v_mfma_f32_16x16x32_bf16 v[38:41], v[192:195], v[216:219], v[38:41]
	v_mfma_f32_16x16x32_bf16 v[34:37], v[200:203], v[216:219], v[34:37]
	v_mfma_f32_16x16x32_bf16 v[22:25], v[192:195], v[224:227], v[22:25]
	v_mfma_f32_16x16x32_bf16 v[18:21], v[200:203], v[224:227], v[18:21]
	v_mfma_f32_16x16x32_bf16 v[6:9], v[192:195], v[232:235], v[6:9]
	v_mfma_f32_16x16x32_bf16 v[2:5], v[200:203], v[232:235], v[2:5]
	s_setprio 0
	s_barrier
	s_add_i32 s25, 0, 0x18000
	v_add_u32_e32 v133, s25, v189
	s_add_i32 s72, 0, 0x1c000
	ds_read_b128 v[148:151], v133
	ds_read_b128 v[152:155], v133 offset:1024
	ds_read_b128 v[156:159], v133 offset:2048
	ds_read_b128 v[160:163], v133 offset:3072
	v_add_u32_e32 v133, s72, v189
	ds_read_b128 v[164:167], v133
	ds_read_b128 v[192:195], v133 offset:1024
	ds_read_b128 v[196:199], v133 offset:2048
	ds_read_b128 v[200:203], v133 offset:3072
	s_add_u32 s4, s4, s82
	s_addc_u32 s5, s5, 0
	s_mov_b32 m0, s76
	v_lshl_add_u64 v[246:247], s[4:5], 0, v[0:1]
	ds_read_b128 v[204:207], v190 offset:32768
	ds_read_b128 v[208:211], v190 offset:33792
	ds_read_b128 v[212:215], v190 offset:34816
	ds_read_b128 v[216:219], v190 offset:35840
	ds_read_b128 v[220:223], v190 offset:36864
	ds_read_b128 v[224:227], v190 offset:37888
	ds_read_b128 v[228:231], v190 offset:38912
	ds_read_b128 v[232:235], v190 offset:39936
	global_load_lds_dwordx4 v[246:247], off
	v_lshl_add_u64 v[246:247], s[4:5], 0, v[130:131]
	s_mov_b32 m0, s77
	s_nop 0
	global_load_lds_dwordx4 v[246:247], off
	s_waitcnt vmcnt(8)
	s_waitcnt lgkmcnt(0)
	s_barrier
	s_setprio 1
	s_waitcnt lgkmcnt(0)
	v_mfma_f32_16x16x32_bf16 v[126:129], v[148:151], v[204:207], v[126:129]
	v_mfma_f32_16x16x32_bf16 v[122:125], v[156:159], v[204:207], v[122:125]
	v_mfma_f32_16x16x32_bf16 v[110:113], v[148:151], v[212:215], v[110:113]
	v_mfma_f32_16x16x32_bf16 v[106:109], v[156:159], v[212:215], v[106:109]
	v_mfma_f32_16x16x32_bf16 v[94:97], v[148:151], v[220:223], v[94:97]
	v_mfma_f32_16x16x32_bf16 v[90:93], v[156:159], v[220:223], v[90:93]
	v_mfma_f32_16x16x32_bf16 v[78:81], v[148:151], v[228:231], v[78:81]
	v_mfma_f32_16x16x32_bf16 v[74:77], v[156:159], v[228:231], v[74:77]
	v_mfma_f32_16x16x32_bf16 v[126:129], v[152:155], v[208:211], v[126:129]
	v_mfma_f32_16x16x32_bf16 v[122:125], v[160:163], v[208:211], v[122:125]
	v_mfma_f32_16x16x32_bf16 v[110:113], v[152:155], v[216:219], v[110:113]
	v_mfma_f32_16x16x32_bf16 v[106:109], v[160:163], v[216:219], v[106:109]
	v_mfma_f32_16x16x32_bf16 v[94:97], v[152:155], v[224:227], v[94:97]
	v_mfma_f32_16x16x32_bf16 v[90:93], v[160:163], v[224:227], v[90:93]
	v_mfma_f32_16x16x32_bf16 v[78:81], v[152:155], v[232:235], v[78:81]
	v_mfma_f32_16x16x32_bf16 v[74:77], v[160:163], v[232:235], v[74:77]
	v_mfma_f32_16x16x32_bf16 v[118:121], v[164:167], v[204:207], v[118:121]
	v_mfma_f32_16x16x32_bf16 v[114:117], v[196:199], v[204:207], v[114:117]
	v_mfma_f32_16x16x32_bf16 v[102:105], v[164:167], v[212:215], v[102:105]
	v_mfma_f32_16x16x32_bf16 v[98:101], v[196:199], v[212:215], v[98:101]
	v_mfma_f32_16x16x32_bf16 v[86:89], v[164:167], v[220:223], v[86:89]
	v_mfma_f32_16x16x32_bf16 v[82:85], v[196:199], v[220:223], v[82:85]
	v_mfma_f32_16x16x32_bf16 v[70:73], v[164:167], v[228:231], v[70:73]
	v_mfma_f32_16x16x32_bf16 v[66:69], v[196:199], v[228:231], v[66:69]
	v_mfma_f32_16x16x32_bf16 v[118:121], v[192:195], v[208:211], v[118:121]
	v_mfma_f32_16x16x32_bf16 v[114:117], v[200:203], v[208:211], v[114:117]
	v_mfma_f32_16x16x32_bf16 v[102:105], v[192:195], v[216:219], v[102:105]
	v_mfma_f32_16x16x32_bf16 v[98:101], v[200:203], v[216:219], v[98:101]
	v_mfma_f32_16x16x32_bf16 v[86:89], v[192:195], v[224:227], v[86:89]
	v_mfma_f32_16x16x32_bf16 v[82:85], v[200:203], v[224:227], v[82:85]
	v_mfma_f32_16x16x32_bf16 v[70:73], v[192:195], v[232:235], v[70:73]
	v_mfma_f32_16x16x32_bf16 v[66:69], v[200:203], v[232:235], v[66:69]
	s_setprio 0
	s_barrier
; #define PG8_STAGE(bufoff, gbase, voff) do { _Pragma("unroll") for (int _i = 0; _i < 2; ++_i) \
;         __builtin_amdgcn_global_load_lds((const unsigned*)((const char*)(gbase) + (voff)[_i]), (LAS unsigned*)(lds + (bufoff) + ldsw + _i * 8192), 16, 0, 0); } while (0)
; #define PG8_LDA(dst, b, h) do { _Pragma("unroll") for (int m = 0; m < 4; ++m) _Pragma("unroll") for (int k = 0; k < 2; ++k) dst[m][k] = *(const LAS bf16x8*)(lds + PG8_SA(b, h) + aoff + m * 2048 + k * 1024); } while (0)
; #define PG8_MMA(ai, bj, At, Bt) do { __builtin_amdgcn_s_setprio(1); _Pragma("unroll") for (int m = 0; m < 4; ++m) _Pragma("unroll") for (int n = 0; n < 2; ++n) _Pragma("unroll") for (int k = 0; k < 2; ++k) \
;         acc[ai][bj][m][n] = __builtin_amdgcn_mfma_f32_16x16x32_bf16(Bt[n][k], At[m][k], acc[ai][bj][m][n], 0, 0, 0); __builtin_amdgcn_s_setprio(0); } while (0)
; #define PG8_WAIT_V(n) asm volatile("s_waitcnt vmcnt(" #n ")" ::: "memory")
; #define PG8_WAIT_L(n) asm volatile("s_waitcnt lgkmcnt(" #n ")" ::: "memory")
; #define PG8_BAR __builtin_amdgcn_s_barrier()
; #define PG8_SCHED __builtin_amdgcn_sched_barrier(0)
; template <class Epi>
; __device__ __forceinline__ void gemm_phase(LAS unsigned char* lds, const Gemm g, const Epi& E) {
;     ...
;             PG8_LDA(At, 1, 1); PG8_STAGE(PG8_SB(1, 0), b3, voffA); PG8_STAGE(PG8_SB(1, 1), b3 + hstep, voffA); PG8_STAGE(PG8_SA(1, 0), a3, voffA);
;             PG8_WAIT_V(8); PG8_WAIT_L(0); PG8_BAR; PG8_MMA(1, 0, At, B0); PG8_MMA(1, 1, At, B1); PG8_BAR; PG8_SCHED;
;         }
;         if (wr == 0) PG8_BAR;
	s_add_i32 s4, s25, s37
	v_lshl_add_u64 v[168:169], v[168:169], 0, s[80:81]
	s_mov_b32 m0, s4
	ds_read_b128 v[204:207], v190 offset:49152
	ds_read_b128 v[208:211], v190 offset:50176
	ds_read_b128 v[212:215], v190 offset:51200
	ds_read_b128 v[216:219], v190 offset:52224
	ds_read_b128 v[220:223], v190 offset:53248
	ds_read_b128 v[224:227], v190 offset:54272
	ds_read_b128 v[228:231], v190 offset:55296
	ds_read_b128 v[232:235], v190 offset:56320
	global_load_lds_dwordx4 v[168:169], off
	v_lshl_add_u64 v[168:169], v[236:237], 0, s[80:81]
	s_add_i32 m0, s4, 0x2000
	s_add_i32 s4, s72, s37
	global_load_lds_dwordx4 v[168:169], off
	v_lshl_add_u64 v[168:169], v[238:239], 0, s[80:81]
	s_mov_b32 m0, s4
	s_nop 0
	global_load_lds_dwordx4 v[168:169], off
	v_lshl_add_u64 v[168:169], v[240:241], 0, s[80:81]
	s_add_i32 m0, s4, 0x2000
	s_nop 0
	global_load_lds_dwordx4 v[168:169], off
	v_lshl_add_u64 v[168:169], v[242:243], 0, s[80:81]
	s_mov_b32 m0, s58
	s_nop 0
	global_load_lds_dwordx4 v[168:169], off
	v_lshl_add_u64 v[168:169], v[244:245], 0, s[80:81]
	s_mov_b32 m0, s59
	s_nop 0
	global_load_lds_dwordx4 v[168:169], off
	s_waitcnt vmcnt(8)
	s_waitcnt lgkmcnt(0)
	s_barrier
	s_setprio 1
	s_waitcnt lgkmcnt(0)
	v_mfma_f32_16x16x32_bf16 v[62:65], v[148:151], v[204:207], v[62:65]
	v_mfma_f32_16x16x32_bf16 v[58:61], v[156:159], v[204:207], v[58:61]
	v_mfma_f32_16x16x32_bf16 v[46:49], v[148:151], v[212:215], v[46:49]
	v_mfma_f32_16x16x32_bf16 v[42:45], v[156:159], v[212:215], v[42:45]
	v_mfma_f32_16x16x32_bf16 v[30:33], v[148:151], v[220:223], v[30:33]
	v_mfma_f32_16x16x32_bf16 v[26:29], v[156:159], v[220:223], v[26:29]
	v_mfma_f32_16x16x32_bf16 v[14:17], v[148:151], v[228:231], v[14:17]
	v_mfma_f32_16x16x32_bf16 v[10:13], v[156:159], v[228:231], v[10:13]
	v_mfma_f32_16x16x32_bf16 v[62:65], v[152:155], v[208:211], v[62:65]
	v_mfma_f32_16x16x32_bf16 v[58:61], v[160:163], v[208:211], v[58:61]
	v_mfma_f32_16x16x32_bf16 v[46:49], v[152:155], v[216:219], v[46:49]
	v_mfma_f32_16x16x32_bf16 v[42:45], v[160:163], v[216:219], v[42:45]
	v_mfma_f32_16x16x32_bf16 v[30:33], v[152:155], v[224:227], v[30:33]
	v_mfma_f32_16x16x32_bf16 v[26:29], v[160:163], v[224:227], v[26:29]
	v_mfma_f32_16x16x32_bf16 v[14:17], v[152:155], v[232:235], v[14:17]
	v_mfma_f32_16x16x32_bf16 v[10:13], v[160:163], v[232:235], v[10:13]
	v_mfma_f32_16x16x32_bf16 v[54:57], v[164:167], v[204:207], v[54:57]
	v_mfma_f32_16x16x32_bf16 v[50:53], v[196:199], v[204:207], v[50:53]
	v_mfma_f32_16x16x32_bf16 v[38:41], v[164:167], v[212:215], v[38:41]
	v_mfma_f32_16x16x32_bf16 v[34:37], v[196:199], v[212:215], v[34:37]
	v_mfma_f32_16x16x32_bf16 v[22:25], v[164:167], v[220:223], v[22:25]
	v_mfma_f32_16x16x32_bf16 v[18:21], v[196:199], v[220:223], v[18:21]
	v_mfma_f32_16x16x32_bf16 v[6:9], v[164:167], v[228:231], v[6:9]
	v_mfma_f32_16x16x32_bf16 v[2:5], v[196:199], v[228:231], v[2:5]
	v_mfma_f32_16x16x32_bf16 v[54:57], v[192:195], v[208:211], v[54:57]
	v_mfma_f32_16x16x32_bf16 v[50:53], v[200:203], v[208:211], v[50:53]
	v_mfma_f32_16x16x32_bf16 v[38:41], v[192:195], v[216:219], v[38:41]
	v_mfma_f32_16x16x32_bf16 v[34:37], v[200:203], v[216:219], v[34:37]
	v_mfma_f32_16x16x32_bf16 v[22:25], v[192:195], v[224:227], v[22:25]
	v_mfma_f32_16x16x32_bf16 v[18:21], v[200:203], v[224:227], v[18:21]
	v_mfma_f32_16x16x32_bf16 v[6:9], v[192:195], v[232:235], v[6:9]
	v_mfma_f32_16x16x32_bf16 v[2:5], v[200:203], v[232:235], v[2:5]
	s_setprio 0
	s_barrier
	s_add_u32 s62, s62, 0x100
	s_addc_u32 s63, s63, 0
	s_add_u32 s15, s15, 0x100
	s_addc_u32 s53, s53, 0
	s_cmp_ge_i32 vcc_lo, s70
	s_mov_b32 s4, vcc_lo
	s_cbranch_scc0 .LBB0_407
	s_and_b64 vcc, exec, s[12:13]
	s_cbranch_vccz .LBB0_410

; #define PG8_STAGE(bufoff, gbase, voff) do { _Pragma("unroll") for (int _i = 0; _i < 2; ++_i) \
;         __builtin_amdgcn_global_load_lds((const unsigned*)((const char*)(gbase) + (voff)[_i]), (LAS unsigned*)(lds + (bufoff) + ldsw + _i * 8192), 16, 0, 0); } while (0)
; #define PG8_LDA(dst, b, h) do { _Pragma("unroll") for (int m = 0; m < 4; ++m) _Pragma("unroll") for (int k = 0; k < 2; ++k) dst[m][k] = *(const LAS bf16x8*)(lds + PG8_SA(b, h) + aoff + m * 2048 + k * 1024); } while (0)
; #define PG8_MMA(ai, bj, At, Bt) do { __builtin_amdgcn_s_setprio(1); _Pragma("unroll") for (int m = 0; m < 4; ++m) _Pragma("unroll") for (int n = 0; n < 2; ++n) _Pragma("unroll") for (int k = 0; k < 2; ++k) \
;         acc[ai][bj][m][n] = __builtin_amdgcn_mfma_f32_16x16x32_bf16(Bt[n][k], At[m][k], acc[ai][bj][m][n], 0, 0, 0); __builtin_amdgcn_s_setprio(0); } while (0)
; #define PG8_WAIT_V(n) asm volatile("s_waitcnt vmcnt(" #n ")" ::: "memory")
; #define PG8_WAIT_L(n) asm volatile("s_waitcnt lgkmcnt(" #n ")" ::: "memory")
; #define PG8_BAR __builtin_amdgcn_s_barrier()
; #define PG8_SCHED __builtin_amdgcn_sched_barrier(0)
; template <class Epi>
; __device__ __forceinline__ void gemm_phase(LAS unsigned char* lds, const Gemm g, const Epi& E) {
;     ...
;             PG8_WAIT_V(8); PG8_WAIT_L(0); PG8_BAR; PG8_MMA(0, 0, At, B0); PG8_MMA(0, 1, At, B1); PG8_BAR; PG8_SCHED;
;             PG8_LDA(At, 0, 1); PG8_STAGE(PG8_SB(0, 0), b2, voffA); PG8_STAGE(PG8_SB(0, 1), b2 + hstep, voffA); PG8_STAGE(PG8_SA(0, 0), a2, voffA);
.Lrw3a_d:
	s_waitcnt lgkmcnt(0)
	s_barrier
	s_setprio 1
	s_waitcnt lgkmcnt(0)
	v_mfma_f32_16x16x32_bf16 v[126:129], v[146:149], v[198:201], v[126:129]
	v_mfma_f32_16x16x32_bf16 v[118:121], v[154:157], v[198:201], v[118:121]
	v_mfma_f32_16x16x32_bf16 v[110:113], v[146:149], v[206:209], v[110:113]
	v_mfma_f32_16x16x32_bf16 v[102:105], v[154:157], v[206:209], v[102:105]
	v_mfma_f32_16x16x32_bf16 v[94:97], v[146:149], v[214:217], v[94:97]
	v_mfma_f32_16x16x32_bf16 v[86:89], v[154:157], v[214:217], v[86:89]
	v_mfma_f32_16x16x32_bf16 v[78:81], v[146:149], v[222:225], v[78:81]
	v_mfma_f32_16x16x32_bf16 v[70:73], v[154:157], v[222:225], v[70:73]
	v_mfma_f32_16x16x32_bf16 v[126:129], v[150:153], v[202:205], v[126:129]
	v_mfma_f32_16x16x32_bf16 v[118:121], v[158:161], v[202:205], v[118:121]
	v_mfma_f32_16x16x32_bf16 v[110:113], v[150:153], v[210:213], v[110:113]
	v_mfma_f32_16x16x32_bf16 v[102:105], v[158:161], v[210:213], v[102:105]
	v_mfma_f32_16x16x32_bf16 v[94:97], v[150:153], v[218:221], v[94:97]
	v_mfma_f32_16x16x32_bf16 v[86:89], v[158:161], v[218:221], v[86:89]
	v_mfma_f32_16x16x32_bf16 v[78:81], v[150:153], v[226:229], v[78:81]
	v_mfma_f32_16x16x32_bf16 v[70:73], v[158:161], v[226:229], v[70:73]
	v_mfma_f32_16x16x32_bf16 v[122:125], v[162:165], v[198:201], v[122:125]
	v_mfma_f32_16x16x32_bf16 v[114:117], v[190:193], v[198:201], v[114:117]
	v_mfma_f32_16x16x32_bf16 v[106:109], v[162:165], v[206:209], v[106:109]
	v_mfma_f32_16x16x32_bf16 v[98:101], v[190:193], v[206:209], v[98:101]
	v_mfma_f32_16x16x32_bf16 v[90:93], v[162:165], v[214:217], v[90:93]
	v_mfma_f32_16x16x32_bf16 v[82:85], v[190:193], v[214:217], v[82:85]
	v_mfma_f32_16x16x32_bf16 v[74:77], v[162:165], v[222:225], v[74:77]
	v_mfma_f32_16x16x32_bf16 v[66:69], v[190:193], v[222:225], v[66:69]
	v_mfma_f32_16x16x32_bf16 v[122:125], v[166:169], v[202:205], v[122:125]
	v_mfma_f32_16x16x32_bf16 v[114:117], v[194:197], v[202:205], v[114:117]
	v_mfma_f32_16x16x32_bf16 v[106:109], v[166:169], v[210:213], v[106:109]
	v_mfma_f32_16x16x32_bf16 v[98:101], v[194:197], v[210:213], v[98:101]
	v_mfma_f32_16x16x32_bf16 v[90:93], v[166:169], v[218:221], v[90:93]
	v_mfma_f32_16x16x32_bf16 v[82:85], v[194:197], v[218:221], v[82:85]
	v_mfma_f32_16x16x32_bf16 v[74:77], v[166:169], v[226:229], v[74:77]
	v_mfma_f32_16x16x32_bf16 v[66:69], v[194:197], v[226:229], v[66:69]
	s_setprio 0
	s_barrier
	s_add_i32 s72, s21, s2
	v_lshl_add_u64 v[136:137], s[4:5], 0, v[0:1]
	s_mov_b32 m0, s72
	ds_read_b128 v[198:201], v145 offset:16384
	ds_read_b128 v[202:205], v145 offset:17408
	ds_read_b128 v[206:209], v145 offset:18432
	ds_read_b128 v[210:213], v145 offset:19456
	ds_read_b128 v[214:217], v145 offset:20480
	ds_read_b128 v[218:221], v145 offset:21504
	ds_read_b128 v[222:225], v145 offset:22528
	ds_read_b128 v[226:229], v145 offset:23552
	global_load_lds_dwordx4 v[136:137], off
	s_add_i32 m0, s72, 0x2000
	s_add_u32 s72, s4, 0x40000
	v_lshl_add_u64 v[230:231], s[4:5], 0, v[130:131]
	s_addc_u32 s73, s5, 0
	s_add_i32 s25, s25, s2
	global_load_lds_dwordx4 v[230:231], off
	v_lshl_add_u64 v[232:233], s[72:73], 0, v[0:1]
	s_mov_b32 m0, s25
	v_lshl_add_u64 v[234:235], s[70:71], 0, v[130:131]
	global_load_lds_dwordx4 v[232:233], off
	v_lshl_add_u64 v[232:233], s[72:73], 0, v[130:131]
	s_add_i32 m0, s25, 0x2000
	s_nop 0
	global_load_lds_dwordx4 v[232:233], off
	v_lshl_add_u64 v[232:233], s[70:71], 0, v[0:1]
	s_mov_b32 m0, s7
	s_nop 0
	global_load_lds_dwordx4 v[232:233], off
	s_mov_b32 m0, s9
	s_nop 0
	global_load_lds_dwordx4 v[234:235], off
	s_cmp_eq_u32 s32, 1
	s_cbranch_scc1 .Lrw3b_1
	s_waitcnt vmcnt(16)
	s_branch .Lrw3b_d

; #define PG8_STAGE(bufoff, gbase, voff) do { _Pragma("unroll") for (int _i = 0; _i < 2; ++_i) \
;         __builtin_amdgcn_global_load_lds((const unsigned*)((const char*)(gbase) + (voff)[_i]), (LAS unsigned*)(lds + (bufoff) + ldsw + _i * 8192), 16, 0, 0); } while (0)
; #define PG8_LDA(dst, b, h) do { _Pragma("unroll") for (int m = 0; m < 4; ++m) _Pragma("unroll") for (int k = 0; k < 2; ++k) dst[m][k] = *(const LAS bf16x8*)(lds + PG8_SA(b, h) + aoff + m * 2048 + k * 1024); } while (0)
; #define PG8_LDB(dst, b, h) do { _Pragma("unroll") for (int n = 0; n < 2; ++n) _Pragma("unroll") for (int k = 0; k < 2; ++k) dst[n][k] = *(const LAS bf16x8*)(lds + PG8_SB(b, h) + boff + n * 2048 + k * 1024); } while (0)
; #define PG8_MMA(ai, bj, At, Bt) do { __builtin_amdgcn_s_setprio(1); _Pragma("unroll") for (int m = 0; m < 4; ++m) _Pragma("unroll") for (int n = 0; n < 2; ++n) _Pragma("unroll") for (int k = 0; k < 2; ++k) \
;         acc[ai][bj][m][n] = __builtin_amdgcn_mfma_f32_16x16x32_bf16(Bt[n][k], At[m][k], acc[ai][bj][m][n], 0, 0, 0); __builtin_amdgcn_s_setprio(0); } while (0)
; #define PG8_WAIT_V(n) asm volatile("s_waitcnt vmcnt(" #n ")" ::: "memory")
; #define PG8_WAIT_L(n) asm volatile("s_waitcnt lgkmcnt(" #n ")" ::: "memory")
; #define PG8_BAR __builtin_amdgcn_s_barrier()
; #define PG8_SCHED __builtin_amdgcn_sched_barrier(0)
; template <class Epi>
; __device__ __forceinline__ void gemm_phase(LAS unsigned char* lds, const Gemm g, const Epi& E) {
;     ...
;             PG8_WAIT_V(8); PG8_WAIT_L(0); PG8_BAR; PG8_MMA(1, 0, At, B0); PG8_MMA(1, 1, At, B1); PG8_BAR; PG8_SCHED;
;             PG8_LDB(B0, 1, 0); PG8_LDB(B1, 1, 1); PG8_SCHED; PG8_LDA(At, 1, 0); PG8_STAGE(PG8_SA(0, 1), a2 + hstep, voffA);
;             PG8_WAIT_V(8); PG8_WAIT_L(0); PG8_BAR; PG8_MMA(0, 0, At, B0); PG8_MMA(0, 1, At, B1); PG8_BAR; PG8_SCHED;
.Lrw3b_d:
	s_mov_b32 s32, 0
	s_waitcnt lgkmcnt(0)
	s_barrier
	s_setprio 1
	s_waitcnt lgkmcnt(0)
	v_mfma_f32_16x16x32_bf16 v[62:65], v[146:149], v[198:201], v[62:65]
	v_mfma_f32_16x16x32_bf16 v[54:57], v[154:157], v[198:201], v[54:57]
	v_mfma_f32_16x16x32_bf16 v[46:49], v[146:149], v[206:209], v[46:49]
	v_mfma_f32_16x16x32_bf16 v[38:41], v[154:157], v[206:209], v[38:41]
	v_mfma_f32_16x16x32_bf16 v[30:33], v[146:149], v[214:217], v[30:33]
	v_mfma_f32_16x16x32_bf16 v[22:25], v[154:157], v[214:217], v[22:25]
	v_mfma_f32_16x16x32_bf16 v[14:17], v[146:149], v[222:225], v[14:17]
	v_mfma_f32_16x16x32_bf16 v[6:9], v[154:157], v[222:225], v[6:9]
	v_mfma_f32_16x16x32_bf16 v[62:65], v[150:153], v[202:205], v[62:65]
	v_mfma_f32_16x16x32_bf16 v[54:57], v[158:161], v[202:205], v[54:57]
	v_mfma_f32_16x16x32_bf16 v[46:49], v[150:153], v[210:213], v[46:49]
	v_mfma_f32_16x16x32_bf16 v[38:41], v[158:161], v[210:213], v[38:41]
	v_mfma_f32_16x16x32_bf16 v[30:33], v[150:153], v[218:221], v[30:33]
	v_mfma_f32_16x16x32_bf16 v[22:25], v[158:161], v[218:221], v[22:25]
	v_mfma_f32_16x16x32_bf16 v[14:17], v[150:153], v[226:229], v[14:17]
	v_mfma_f32_16x16x32_bf16 v[6:9], v[158:161], v[226:229], v[6:9]
	v_mfma_f32_16x16x32_bf16 v[58:61], v[162:165], v[198:201], v[58:61]
	v_mfma_f32_16x16x32_bf16 v[50:53], v[190:193], v[198:201], v[50:53]
	v_mfma_f32_16x16x32_bf16 v[42:45], v[162:165], v[206:209], v[42:45]
	v_mfma_f32_16x16x32_bf16 v[34:37], v[190:193], v[206:209], v[34:37]
	v_mfma_f32_16x16x32_bf16 v[26:29], v[162:165], v[214:217], v[26:29]
	v_mfma_f32_16x16x32_bf16 v[18:21], v[190:193], v[214:217], v[18:21]
	v_mfma_f32_16x16x32_bf16 v[10:13], v[162:165], v[222:225], v[10:13]
	v_mfma_f32_16x16x32_bf16 v[2:5], v[190:193], v[222:225], v[2:5]
	v_mfma_f32_16x16x32_bf16 v[58:61], v[166:169], v[202:205], v[58:61]
	v_mfma_f32_16x16x32_bf16 v[50:53], v[194:197], v[202:205], v[50:53]
	v_mfma_f32_16x16x32_bf16 v[42:45], v[166:169], v[210:213], v[42:45]
	v_mfma_f32_16x16x32_bf16 v[34:37], v[194:197], v[210:213], v[34:37]
	v_mfma_f32_16x16x32_bf16 v[26:29], v[166:169], v[218:221], v[26:29]
	v_mfma_f32_16x16x32_bf16 v[18:21], v[194:197], v[218:221], v[18:21]
	v_mfma_f32_16x16x32_bf16 v[10:13], v[166:169], v[226:229], v[10:13]
	v_mfma_f32_16x16x32_bf16 v[2:5], v[194:197], v[226:229], v[2:5]
	s_setprio 0
	s_barrier
	s_add_i32 s25, 0, 0x18000
	s_add_i32 s72, 0, 0x1c000
	v_add_u32_e32 v158, s25, v144
	v_add_u32_e32 v189, s72, v144
	ds_read_b128 v[146:149], v158
	ds_read_b128 v[150:153], v158 offset:1024
	ds_read_b128 v[154:157], v158 offset:2048
	ds_read_b128 v[158:161], v158 offset:3072
	ds_read_b128 v[162:165], v189
	ds_read_b128 v[166:169], v189 offset:1024
	ds_read_b128 v[190:193], v189 offset:2048
	ds_read_b128 v[194:197], v189 offset:3072
	s_add_u32 s70, s70, 0x40000
	s_addc_u32 s71, s71, 0
	s_mov_b32 m0, s45
	v_lshl_add_u64 v[236:237], s[70:71], 0, v[0:1]
	ds_read_b128 v[198:201], v145 offset:32768
	ds_read_b128 v[202:205], v145 offset:33792
	ds_read_b128 v[206:209], v145 offset:34816
	ds_read_b128 v[210:213], v145 offset:35840
	ds_read_b128 v[214:217], v145 offset:36864
	ds_read_b128 v[218:221], v145 offset:37888
	ds_read_b128 v[222:225], v145 offset:38912
	ds_read_b128 v[226:229], v145 offset:39936
	global_load_lds_dwordx4 v[236:237], off
	v_lshl_add_u64 v[236:237], s[70:71], 0, v[130:131]
	s_mov_b32 m0, s52
	s_nop 0
	global_load_lds_dwordx4 v[236:237], off
	s_waitcnt vmcnt(8)
	s_waitcnt lgkmcnt(0)
	s_barrier
	s_setprio 1
	s_waitcnt lgkmcnt(0)
	v_mfma_f32_16x16x32_bf16 v[126:129], v[146:149], v[198:201], v[126:129]
	v_mfma_f32_16x16x32_bf16 v[118:121], v[154:157], v[198:201], v[118:121]
	v_mfma_f32_16x16x32_bf16 v[110:113], v[146:149], v[206:209], v[110:113]
	v_mfma_f32_16x16x32_bf16 v[102:105], v[154:157], v[206:209], v[102:105]
	v_mfma_f32_16x16x32_bf16 v[94:97], v[146:149], v[214:217], v[94:97]
	v_mfma_f32_16x16x32_bf16 v[86:89], v[154:157], v[214:217], v[86:89]
	v_mfma_f32_16x16x32_bf16 v[78:81], v[146:149], v[222:225], v[78:81]
	v_mfma_f32_16x16x32_bf16 v[70:73], v[154:157], v[222:225], v[70:73]
	v_mfma_f32_16x16x32_bf16 v[126:129], v[150:153], v[202:205], v[126:129]
	v_mfma_f32_16x16x32_bf16 v[118:121], v[158:161], v[202:205], v[118:121]
	v_mfma_f32_16x16x32_bf16 v[110:113], v[150:153], v[210:213], v[110:113]
	v_mfma_f32_16x16x32_bf16 v[102:105], v[158:161], v[210:213], v[102:105]
	v_mfma_f32_16x16x32_bf16 v[94:97], v[150:153], v[218:221], v[94:97]
	v_mfma_f32_16x16x32_bf16 v[86:89], v[158:161], v[218:221], v[86:89]
	v_mfma_f32_16x16x32_bf16 v[78:81], v[150:153], v[226:229], v[78:81]
	v_mfma_f32_16x16x32_bf16 v[70:73], v[158:161], v[226:229], v[70:73]
	v_mfma_f32_16x16x32_bf16 v[122:125], v[162:165], v[198:201], v[122:125]
	v_mfma_f32_16x16x32_bf16 v[114:117], v[190:193], v[198:201], v[114:117]
	v_mfma_f32_16x16x32_bf16 v[106:109], v[162:165], v[206:209], v[106:109]
	v_mfma_f32_16x16x32_bf16 v[98:101], v[190:193], v[206:209], v[98:101]
	v_mfma_f32_16x16x32_bf16 v[90:93], v[162:165], v[214:217], v[90:93]
	v_mfma_f32_16x16x32_bf16 v[82:85], v[190:193], v[214:217], v[82:85]
	v_mfma_f32_16x16x32_bf16 v[74:77], v[162:165], v[222:225], v[74:77]
	v_mfma_f32_16x16x32_bf16 v[66:69], v[190:193], v[222:225], v[66:69]
	v_mfma_f32_16x16x32_bf16 v[122:125], v[166:169], v[202:205], v[122:125]
	v_mfma_f32_16x16x32_bf16 v[114:117], v[194:197], v[202:205], v[114:117]
	v_mfma_f32_16x16x32_bf16 v[106:109], v[166:169], v[210:213], v[106:109]
	v_mfma_f32_16x16x32_bf16 v[98:101], v[194:197], v[210:213], v[98:101]
	v_mfma_f32_16x16x32_bf16 v[90:93], v[166:169], v[218:221], v[90:93]
	v_mfma_f32_16x16x32_bf16 v[82:85], v[194:197], v[218:221], v[82:85]
	v_mfma_f32_16x16x32_bf16 v[74:77], v[166:169], v[226:229], v[74:77]
	v_mfma_f32_16x16x32_bf16 v[66:69], v[194:197], v[226:229], v[66:69]
	s_setprio 0
	s_barrier
; #define PG8_STAGE(bufoff, gbase, voff) do { _Pragma("unroll") for (int _i = 0; _i < 2; ++_i) \
;         __builtin_amdgcn_global_load_lds((const unsigned*)((const char*)(gbase) + (voff)[_i]), (LAS unsigned*)(lds + (bufoff) + ldsw + _i * 8192), 16, 0, 0); } while (0)
; #define PG8_LDA(dst, b, h) do { _Pragma("unroll") for (int m = 0; m < 4; ++m) _Pragma("unroll") for (int k = 0; k < 2; ++k) dst[m][k] = *(const LAS bf16x8*)(lds + PG8_SA(b, h) + aoff + m * 2048 + k * 1024); } while (0)
; #define PG8_MMA(ai, bj, At, Bt) do { __builtin_amdgcn_s_setprio(1); _Pragma("unroll") for (int m = 0; m < 4; ++m) _Pragma("unroll") for (int n = 0; n < 2; ++n) _Pragma("unroll") for (int k = 0; k < 2; ++k) \
;         acc[ai][bj][m][n] = __builtin_amdgcn_mfma_f32_16x16x32_bf16(Bt[n][k], At[m][k], acc[ai][bj][m][n], 0, 0, 0); __builtin_amdgcn_s_setprio(0); } while (0)
; #define PG8_WAIT_V(n) asm volatile("s_waitcnt vmcnt(" #n ")" ::: "memory")
; #define PG8_WAIT_L(n) asm volatile("s_waitcnt lgkmcnt(" #n ")" ::: "memory")
; #define PG8_BAR __builtin_amdgcn_s_barrier()
; #define PG8_SCHED __builtin_amdgcn_sched_barrier(0)
; template <class Epi>
; __device__ __forceinline__ void gemm_phase(LAS unsigned char* lds, const Gemm g, const Epi& E) {
;     ...
;             PG8_LDA(At, 1, 1); PG8_STAGE(PG8_SB(1, 0), b3, voffA); PG8_STAGE(PG8_SB(1, 1), b3 + hstep, voffA); PG8_STAGE(PG8_SA(1, 0), a3, voffA);
;             PG8_WAIT_V(8); PG8_WAIT_L(0); PG8_BAR; PG8_MMA(1, 0, At, B0); PG8_MMA(1, 1, At, B1); PG8_BAR; PG8_SCHED;
	s_add_i32 s25, s25, s2
	v_lshl_add_u64 v[136:137], v[136:137], 0, s[80:81]
	s_mov_b32 m0, s25
	ds_read_b128 v[198:201], v145 offset:49152
	ds_read_b128 v[202:205], v145 offset:50176
	ds_read_b128 v[206:209], v145 offset:51200
	ds_read_b128 v[210:213], v145 offset:52224
	ds_read_b128 v[214:217], v145 offset:53248
	ds_read_b128 v[218:221], v145 offset:54272
	ds_read_b128 v[222:225], v145 offset:55296
	ds_read_b128 v[226:229], v145 offset:56320
	global_load_lds_dwordx4 v[136:137], off
	s_add_i32 m0, s25, 0x2000
	s_add_u32 s4, s4, 0x40080
	v_lshl_add_u64 v[136:137], v[230:231], 0, s[80:81]
	s_addc_u32 s5, s5, 0
	s_add_i32 s25, s72, s2
	global_load_lds_dwordx4 v[136:137], off
	v_lshl_add_u64 v[136:137], s[4:5], 0, v[0:1]
	s_mov_b32 m0, s25
	s_nop 0
	global_load_lds_dwordx4 v[136:137], off
	v_lshl_add_u64 v[136:137], s[4:5], 0, v[130:131]
	s_add_i32 m0, s25, 0x2000
	s_nop 0
	global_load_lds_dwordx4 v[136:137], off
	v_lshl_add_u64 v[136:137], v[232:233], 0, s[80:81]
	s_mov_b32 m0, s75
	s_nop 0
	global_load_lds_dwordx4 v[136:137], off
	v_lshl_add_u64 v[136:137], v[234:235], 0, s[80:81]
	s_mov_b32 m0, s76
	s_nop 0
	global_load_lds_dwordx4 v[136:137], off
	s_waitcnt vmcnt(8)
	s_waitcnt lgkmcnt(0)
	s_barrier
	s_setprio 1
	s_waitcnt lgkmcnt(0)
	v_mfma_f32_16x16x32_bf16 v[62:65], v[146:149], v[198:201], v[62:65]
	v_mfma_f32_16x16x32_bf16 v[54:57], v[154:157], v[198:201], v[54:57]
	v_mfma_f32_16x16x32_bf16 v[46:49], v[146:149], v[206:209], v[46:49]
	v_mfma_f32_16x16x32_bf16 v[38:41], v[154:157], v[206:209], v[38:41]
	v_mfma_f32_16x16x32_bf16 v[30:33], v[146:149], v[214:217], v[30:33]
	v_mfma_f32_16x16x32_bf16 v[22:25], v[154:157], v[214:217], v[22:25]
	v_mfma_f32_16x16x32_bf16 v[14:17], v[146:149], v[222:225], v[14:17]
	v_mfma_f32_16x16x32_bf16 v[6:9], v[154:157], v[222:225], v[6:9]
	v_mfma_f32_16x16x32_bf16 v[62:65], v[150:153], v[202:205], v[62:65]
	v_mfma_f32_16x16x32_bf16 v[54:57], v[158:161], v[202:205], v[54:57]
	v_mfma_f32_16x16x32_bf16 v[46:49], v[150:153], v[210:213], v[46:49]
	v_mfma_f32_16x16x32_bf16 v[38:41], v[158:161], v[210:213], v[38:41]
	v_mfma_f32_16x16x32_bf16 v[30:33], v[150:153], v[218:221], v[30:33]
	v_mfma_f32_16x16x32_bf16 v[22:25], v[158:161], v[218:221], v[22:25]
	v_mfma_f32_16x16x32_bf16 v[14:17], v[150:153], v[226:229], v[14:17]
	v_mfma_f32_16x16x32_bf16 v[6:9], v[158:161], v[226:229], v[6:9]
	v_mfma_f32_16x16x32_bf16 v[58:61], v[162:165], v[198:201], v[58:61]
	v_mfma_f32_16x16x32_bf16 v[50:53], v[190:193], v[198:201], v[50:53]
	v_mfma_f32_16x16x32_bf16 v[42:45], v[162:165], v[206:209], v[42:45]
	v_mfma_f32_16x16x32_bf16 v[34:37], v[190:193], v[206:209], v[34:37]
	v_mfma_f32_16x16x32_bf16 v[26:29], v[162:165], v[214:217], v[26:29]
	v_mfma_f32_16x16x32_bf16 v[18:21], v[190:193], v[214:217], v[18:21]
	v_mfma_f32_16x16x32_bf16 v[10:13], v[162:165], v[222:225], v[10:13]
	v_mfma_f32_16x16x32_bf16 v[2:5], v[190:193], v[222:225], v[2:5]
	v_mfma_f32_16x16x32_bf16 v[58:61], v[166:169], v[202:205], v[58:61]
	v_mfma_f32_16x16x32_bf16 v[50:53], v[194:197], v[202:205], v[50:53]
	v_mfma_f32_16x16x32_bf16 v[42:45], v[166:169], v[210:213], v[42:45]
	v_mfma_f32_16x16x32_bf16 v[34:37], v[194:197], v[210:213], v[34:37]
	v_mfma_f32_16x16x32_bf16 v[26:29], v[166:169], v[218:221], v[26:29]
	v_mfma_f32_16x16x32_bf16 v[18:21], v[194:197], v[218:221], v[18:21]
	v_mfma_f32_16x16x32_bf16 v[10:13], v[166:169], v[226:229], v[10:13]
	v_mfma_f32_16x16x32_bf16 v[2:5], v[194:197], v[226:229], v[2:5]
	s_setprio 0
	s_barrier
	s_add_u32 s68, s68, 0x100
	s_addc_u32 s69, s69, 0
	s_add_u32 s93, s93, 0x100
	s_addc_u32 vcc_lo, vcc_lo, 0
	s_cmp_ge_i32 vcc_hi, s37
	s_mov_b32 s4, vcc_hi
	s_cbranch_scc0 .LBB0_441
	s_branch .Lk3_exit

; #define PG8_STAGE(bufoff, gbase, voff) do { _Pragma("unroll") for (int _i = 0; _i < 2; ++_i) \
;         __builtin_amdgcn_global_load_lds((const unsigned*)((const char*)(gbase) + (voff)[_i]), (LAS unsigned*)(lds + (bufoff) + ldsw + _i * 8192), 16, 0, 0); } while (0)
; #define PG8_LDA(dst, b, h) do { _Pragma("unroll") for (int m = 0; m < 4; ++m) _Pragma("unroll") for (int k = 0; k < 2; ++k) dst[m][k] = *(const LAS bf16x8*)(lds + PG8_SA(b, h) + aoff + m * 2048 + k * 1024); } while (0)
; #define PG8_LDB(dst, b, h) do { _Pragma("unroll") for (int n = 0; n < 2; ++n) _Pragma("unroll") for (int k = 0; k < 2; ++k) dst[n][k] = *(const LAS bf16x8*)(lds + PG8_SB(b, h) + boff + n * 2048 + k * 1024); } while (0)
; #define PG8_MMA(ai, bj, At, Bt) do { __builtin_amdgcn_s_setprio(1); _Pragma("unroll") for (int m = 0; m < 4; ++m) _Pragma("unroll") for (int n = 0; n < 2; ++n) _Pragma("unroll") for (int k = 0; k < 2; ++k) \
;         acc[ai][bj][m][n] = __builtin_amdgcn_mfma_f32_16x16x32_bf16(Bt[n][k], At[m][k], acc[ai][bj][m][n], 0, 0, 0); __builtin_amdgcn_s_setprio(0); } while (0)
; #define PG8_WAIT_V(n) asm volatile("s_waitcnt vmcnt(" #n ")" ::: "memory")
; #define PG8_WAIT_L(n) asm volatile("s_waitcnt lgkmcnt(" #n ")" ::: "memory")
; #define PG8_BAR __builtin_amdgcn_s_barrier()
; #define PG8_SCHED __builtin_amdgcn_sched_barrier(0)
; template <class Epi>
; __device__ __forceinline__ void gemm_phase(LAS unsigned char* lds, const Gemm g, const Epi& E) {
;     ...
;             const bool last = (t == nt - 2);
;             const char* a1 = cA + (size_t)(t + 1) * kstep;
;             const char* a2 = last ? nA : cA + (size_t)(t + 2) * kstep; const char* b2 = last ? nB : cB + (size_t)(t + 2) * kstep;
;             const char* a3 = a2 + kstep; const char* b3 = b2 + kstep;
;             PG8_LDB(B0, 0, 0); PG8_LDB(B1, 0, 1); PG8_SCHED; PG8_LDA(At, 0, 0); PG8_STAGE(PG8_SA(1, 1), a1 + hstep, voffA);
;             PG8_WAIT_V(8); PG8_WAIT_L(0); PG8_BAR; PG8_MMA(0, 0, At, B0); PG8_MMA(0, 1, At, B1); PG8_BAR; PG8_SCHED;
;             PG8_LDA(At, 0, 1); PG8_STAGE(PG8_SB(0, 0), b2, voffA); PG8_STAGE(PG8_SB(0, 1), b2 + hstep, voffA); PG8_STAGE(PG8_SA(0, 0), a2, voffA);
;             PG8_WAIT_V(8); PG8_WAIT_L(0); PG8_BAR; PG8_MMA(1, 0, At, B0); PG8_MMA(1, 1, At, B1); PG8_BAR; PG8_SCHED;
.LBB0_441:
	s_add_i32 vcc_hi, s4, 2
	s_add_u32 s5, s68, 0xfffc0080
	s_addc_u32 s70, s69, -1
	s_cmp_eq_u32 s92, s4
	s_cselect_b32 s71, s15, s70
	s_cselect_b32 s70, s55, s5
	v_add_u32_e32 v136, s21, v144
	s_cselect_b32 s5, s57, vcc_lo
	s_cselect_b32 s4, s82, s93
	s_add_i32 s25, 0, 0x14000
	ds_read_b128 v[146:149], v136
	ds_read_b128 v[150:153], v136 offset:1024
	ds_read_b128 v[154:157], v136 offset:2048
	ds_read_b128 v[158:161], v136 offset:3072
	v_add_u32_e32 v136, s25, v144
	ds_read_b128 v[162:165], v136
	ds_read_b128 v[166:169], v136 offset:1024
	ds_read_b128 v[190:193], v136 offset:2048
	ds_read_b128 v[194:197], v136 offset:3072
	v_lshl_add_u64 v[136:137], s[68:69], 0, v[132:133]
	s_add_i32 m0, s7, 0xc000
	ds_read_b128 v[198:201], v145
	ds_read_b128 v[202:205], v145 offset:1024
	ds_read_b128 v[206:209], v145 offset:2048
	ds_read_b128 v[210:213], v145 offset:3072
	ds_read_b128 v[214:217], v145 offset:4096
	ds_read_b128 v[218:221], v145 offset:5120
	ds_read_b128 v[222:225], v145 offset:6144
	ds_read_b128 v[226:229], v145 offset:7168
	global_load_lds_dwordx4 v[136:137], off
	v_lshl_add_u64 v[136:137], s[68:69], 0, v[134:135]
	s_add_i32 m0, s7, 0xe000
	s_nop 0
	global_load_lds_dwordx4 v[136:137], off
	s_waitcnt vmcnt(8)
	s_waitcnt lgkmcnt(0)
	s_barrier
	s_setprio 1
	s_waitcnt lgkmcnt(0)
	v_mfma_f32_16x16x32_bf16 v[126:129], v[146:149], v[198:201], v[126:129]
	v_mfma_f32_16x16x32_bf16 v[118:121], v[154:157], v[198:201], v[118:121]
	v_mfma_f32_16x16x32_bf16 v[110:113], v[146:149], v[206:209], v[110:113]
	v_mfma_f32_16x16x32_bf16 v[102:105], v[154:157], v[206:209], v[102:105]
	v_mfma_f32_16x16x32_bf16 v[94:97], v[146:149], v[214:217], v[94:97]
	v_mfma_f32_16x16x32_bf16 v[86:89], v[154:157], v[214:217], v[86:89]
	v_mfma_f32_16x16x32_bf16 v[78:81], v[146:149], v[222:225], v[78:81]
	v_mfma_f32_16x16x32_bf16 v[70:73], v[154:157], v[222:225], v[70:73]
	v_mfma_f32_16x16x32_bf16 v[126:129], v[150:153], v[202:205], v[126:129]
	v_mfma_f32_16x16x32_bf16 v[118:121], v[158:161], v[202:205], v[118:121]
	v_mfma_f32_16x16x32_bf16 v[110:113], v[150:153], v[210:213], v[110:113]
	v_mfma_f32_16x16x32_bf16 v[102:105], v[158:161], v[210:213], v[102:105]
	v_mfma_f32_16x16x32_bf16 v[94:97], v[150:153], v[218:221], v[94:97]
	v_mfma_f32_16x16x32_bf16 v[86:89], v[158:161], v[218:221], v[86:89]
	v_mfma_f32_16x16x32_bf16 v[78:81], v[150:153], v[226:229], v[78:81]
	v_mfma_f32_16x16x32_bf16 v[70:73], v[158:161], v[226:229], v[70:73]
	v_mfma_f32_16x16x32_bf16 v[122:125], v[162:165], v[198:201], v[122:125]
	v_mfma_f32_16x16x32_bf16 v[114:117], v[190:193], v[198:201], v[114:117]
	v_mfma_f32_16x16x32_bf16 v[106:109], v[162:165], v[206:209], v[106:109]
	v_mfma_f32_16x16x32_bf16 v[98:101], v[190:193], v[206:209], v[98:101]
	v_mfma_f32_16x16x32_bf16 v[90:93], v[162:165], v[214:217], v[90:93]
	v_mfma_f32_16x16x32_bf16 v[82:85], v[190:193], v[214:217], v[82:85]
	v_mfma_f32_16x16x32_bf16 v[74:77], v[162:165], v[222:225], v[74:77]
	v_mfma_f32_16x16x32_bf16 v[66:69], v[190:193], v[222:225], v[66:69]
	v_mfma_f32_16x16x32_bf16 v[122:125], v[166:169], v[202:205], v[122:125]
	v_mfma_f32_16x16x32_bf16 v[114:117], v[194:197], v[202:205], v[114:117]
	v_mfma_f32_16x16x32_bf16 v[106:109], v[166:169], v[210:213], v[106:109]
	v_mfma_f32_16x16x32_bf16 v[98:101], v[194:197], v[210:213], v[98:101]
	v_mfma_f32_16x16x32_bf16 v[90:93], v[166:169], v[218:221], v[90:93]
	v_mfma_f32_16x16x32_bf16 v[82:85], v[194:197], v[218:221], v[82:85]
	v_mfma_f32_16x16x32_bf16 v[74:77], v[166:169], v[226:229], v[74:77]
	v_mfma_f32_16x16x32_bf16 v[66:69], v[194:197], v[226:229], v[66:69]
	s_setprio 0
	s_barrier
	s_add_i32 s72, s21, s2
	v_lshl_add_u64 v[136:137], s[4:5], 0, v[0:1]
	s_mov_b32 m0, s72
	ds_read_b128 v[198:201], v145 offset:16384
	ds_read_b128 v[202:205], v145 offset:17408
	ds_read_b128 v[206:209], v145 offset:18432
	ds_read_b128 v[210:213], v145 offset:19456
	ds_read_b128 v[214:217], v145 offset:20480
	ds_read_b128 v[218:221], v145 offset:21504
	ds_read_b128 v[222:225], v145 offset:22528
	ds_read_b128 v[226:229], v145 offset:23552
	global_load_lds_dwordx4 v[136:137], off
	s_add_i32 m0, s72, 0x2000
	s_add_u32 s72, s4, 0x40000
	v_lshl_add_u64 v[230:231], s[4:5], 0, v[130:131]
	s_addc_u32 s73, s5, 0
	s_add_i32 s25, s25, s2
	global_load_lds_dwordx4 v[230:231], off
	v_lshl_add_u64 v[232:233], s[72:73], 0, v[0:1]
	s_mov_b32 m0, s25
	v_lshl_add_u64 v[234:235], s[70:71], 0, v[130:131]
	global_load_lds_dwordx4 v[232:233], off
	v_lshl_add_u64 v[232:233], s[72:73], 0, v[130:131]
	s_add_i32 m0, s25, 0x2000
	s_nop 0
	global_load_lds_dwordx4 v[232:233], off
	v_lshl_add_u64 v[232:233], s[70:71], 0, v[0:1]
	s_mov_b32 m0, s7
	s_nop 0
	global_load_lds_dwordx4 v[232:233], off
	s_mov_b32 m0, s9
	s_nop 0
	global_load_lds_dwordx4 v[234:235], off
	s_waitcnt vmcnt(8)
	s_waitcnt lgkmcnt(0)
	s_barrier
; #define PG8_STAGE(bufoff, gbase, voff) do { _Pragma("unroll") for (int _i = 0; _i < 2; ++_i) \
;         __builtin_amdgcn_global_load_lds((const unsigned*)((const char*)(gbase) + (voff)[_i]), (LAS unsigned*)(lds + (bufoff) + ldsw + _i * 8192), 16, 0, 0); } while (0)
; #define PG8_LDA(dst, b, h) do { _Pragma("unroll") for (int m = 0; m < 4; ++m) _Pragma("unroll") for (int k = 0; k < 2; ++k) dst[m][k] = *(const LAS bf16x8*)(lds + PG8_SA(b, h) + aoff + m * 2048 + k * 1024); } while (0)
; #define PG8_LDB(dst, b, h) do { _Pragma("unroll") for (int n = 0; n < 2; ++n) _Pragma("unroll") for (int k = 0; k < 2; ++k) dst[n][k] = *(const LAS bf16x8*)(lds + PG8_SB(b, h) + boff + n * 2048 + k * 1024); } while (0)
; #define PG8_MMA(ai, bj, At, Bt) do { __builtin_amdgcn_s_setprio(1); _Pragma("unroll") for (int m = 0; m < 4; ++m) _Pragma("unroll") for (int n = 0; n < 2; ++n) _Pragma("unroll") for (int k = 0; k < 2; ++k) \
;         acc[ai][bj][m][n] = __builtin_amdgcn_mfma_f32_16x16x32_bf16(Bt[n][k], At[m][k], acc[ai][bj][m][n], 0, 0, 0); __builtin_amdgcn_s_setprio(0); } while (0)
; #define PG8_WAIT_V(n) asm volatile("s_waitcnt vmcnt(" #n ")" ::: "memory")
; #define PG8_WAIT_L(n) asm volatile("s_waitcnt lgkmcnt(" #n ")" ::: "memory")
; #define PG8_BAR __builtin_amdgcn_s_barrier()
; #define PG8_SCHED __builtin_amdgcn_sched_barrier(0)
; template <class Epi>
; __device__ __forceinline__ void gemm_phase(LAS unsigned char* lds, const Gemm g, const Epi& E) {
;     ...
;             PG8_WAIT_V(8); PG8_WAIT_L(0); PG8_BAR; PG8_MMA(1, 0, At, B0); PG8_MMA(1, 1, At, B1); PG8_BAR; PG8_SCHED;
;             PG8_LDB(B0, 1, 0); PG8_LDB(B1, 1, 1); PG8_SCHED; PG8_LDA(At, 1, 0); PG8_STAGE(PG8_SA(0, 1), a2 + hstep, voffA);
;             PG8_WAIT_V(8); PG8_WAIT_L(0); PG8_BAR; PG8_MMA(0, 0, At, B0); PG8_MMA(0, 1, At, B1); PG8_BAR; PG8_SCHED;
	s_setprio 1
	s_waitcnt lgkmcnt(0)
	v_mfma_f32_16x16x32_bf16 v[62:65], v[146:149], v[198:201], v[62:65]
	v_mfma_f32_16x16x32_bf16 v[54:57], v[154:157], v[198:201], v[54:57]
	v_mfma_f32_16x16x32_bf16 v[46:49], v[146:149], v[206:209], v[46:49]
	v_mfma_f32_16x16x32_bf16 v[38:41], v[154:157], v[206:209], v[38:41]
	v_mfma_f32_16x16x32_bf16 v[30:33], v[146:149], v[214:217], v[30:33]
	v_mfma_f32_16x16x32_bf16 v[22:25], v[154:157], v[214:217], v[22:25]
	v_mfma_f32_16x16x32_bf16 v[14:17], v[146:149], v[222:225], v[14:17]
	v_mfma_f32_16x16x32_bf16 v[6:9], v[154:157], v[222:225], v[6:9]
	v_mfma_f32_16x16x32_bf16 v[62:65], v[150:153], v[202:205], v[62:65]
	v_mfma_f32_16x16x32_bf16 v[54:57], v[158:161], v[202:205], v[54:57]
	v_mfma_f32_16x16x32_bf16 v[46:49], v[150:153], v[210:213], v[46:49]
	v_mfma_f32_16x16x32_bf16 v[38:41], v[158:161], v[210:213], v[38:41]
	v_mfma_f32_16x16x32_bf16 v[30:33], v[150:153], v[218:221], v[30:33]
	v_mfma_f32_16x16x32_bf16 v[22:25], v[158:161], v[218:221], v[22:25]
	v_mfma_f32_16x16x32_bf16 v[14:17], v[150:153], v[226:229], v[14:17]
	v_mfma_f32_16x16x32_bf16 v[6:9], v[158:161], v[226:229], v[6:9]
	v_mfma_f32_16x16x32_bf16 v[58:61], v[162:165], v[198:201], v[58:61]
	v_mfma_f32_16x16x32_bf16 v[50:53], v[190:193], v[198:201], v[50:53]
	v_mfma_f32_16x16x32_bf16 v[42:45], v[162:165], v[206:209], v[42:45]
	v_mfma_f32_16x16x32_bf16 v[34:37], v[190:193], v[206:209], v[34:37]
	v_mfma_f32_16x16x32_bf16 v[26:29], v[162:165], v[214:217], v[26:29]
	v_mfma_f32_16x16x32_bf16 v[18:21], v[190:193], v[214:217], v[18:21]
	v_mfma_f32_16x16x32_bf16 v[10:13], v[162:165], v[222:225], v[10:13]
	v_mfma_f32_16x16x32_bf16 v[2:5], v[190:193], v[222:225], v[2:5]
	v_mfma_f32_16x16x32_bf16 v[58:61], v[166:169], v[202:205], v[58:61]
	v_mfma_f32_16x16x32_bf16 v[50:53], v[194:197], v[202:205], v[50:53]
	v_mfma_f32_16x16x32_bf16 v[42:45], v[166:169], v[210:213], v[42:45]
	v_mfma_f32_16x16x32_bf16 v[34:37], v[194:197], v[210:213], v[34:37]
	v_mfma_f32_16x16x32_bf16 v[26:29], v[166:169], v[218:221], v[26:29]
	v_mfma_f32_16x16x32_bf16 v[18:21], v[194:197], v[218:221], v[18:21]
	v_mfma_f32_16x16x32_bf16 v[10:13], v[166:169], v[226:229], v[10:13]
	v_mfma_f32_16x16x32_bf16 v[2:5], v[194:197], v[226:229], v[2:5]
	s_setprio 0
	s_barrier
	s_add_i32 s25, 0, 0x18000
	s_add_i32 s72, 0, 0x1c000
	v_add_u32_e32 v158, s25, v144
	v_add_u32_e32 v189, s72, v144
	ds_read_b128 v[146:149], v158
	ds_read_b128 v[150:153], v158 offset:1024
	ds_read_b128 v[154:157], v158 offset:2048
	ds_read_b128 v[158:161], v158 offset:3072
	ds_read_b128 v[162:165], v189
	ds_read_b128 v[166:169], v189 offset:1024
	ds_read_b128 v[190:193], v189 offset:2048
	ds_read_b128 v[194:197], v189 offset:3072
	s_add_u32 s70, s70, 0x40000
	s_addc_u32 s71, s71, 0
	s_mov_b32 m0, s45
	v_lshl_add_u64 v[236:237], s[70:71], 0, v[0:1]
	ds_read_b128 v[198:201], v145 offset:32768
	ds_read_b128 v[202:205], v145 offset:33792
	ds_read_b128 v[206:209], v145 offset:34816
	ds_read_b128 v[210:213], v145 offset:35840
	ds_read_b128 v[214:217], v145 offset:36864
	ds_read_b128 v[218:221], v145 offset:37888
	ds_read_b128 v[222:225], v145 offset:38912
	ds_read_b128 v[226:229], v145 offset:39936
	global_load_lds_dwordx4 v[236:237], off
	v_lshl_add_u64 v[236:237], s[70:71], 0, v[130:131]
	s_mov_b32 m0, s52
	s_nop 0
	global_load_lds_dwordx4 v[236:237], off
	s_waitcnt vmcnt(8)
	s_waitcnt lgkmcnt(0)
	s_barrier
	s_setprio 1
	s_waitcnt lgkmcnt(0)
	v_mfma_f32_16x16x32_bf16 v[126:129], v[146:149], v[198:201], v[126:129]
	v_mfma_f32_16x16x32_bf16 v[118:121], v[154:157], v[198:201], v[118:121]
	v_mfma_f32_16x16x32_bf16 v[110:113], v[146:149], v[206:209], v[110:113]
	v_mfma_f32_16x16x32_bf16 v[102:105], v[154:157], v[206:209], v[102:105]
	v_mfma_f32_16x16x32_bf16 v[94:97], v[146:149], v[214:217], v[94:97]
	v_mfma_f32_16x16x32_bf16 v[86:89], v[154:157], v[214:217], v[86:89]
	v_mfma_f32_16x16x32_bf16 v[78:81], v[146:149], v[222:225], v[78:81]
	v_mfma_f32_16x16x32_bf16 v[70:73], v[154:157], v[222:225], v[70:73]
	v_mfma_f32_16x16x32_bf16 v[126:129], v[150:153], v[202:205], v[126:129]
	v_mfma_f32_16x16x32_bf16 v[118:121], v[158:161], v[202:205], v[118:121]
	v_mfma_f32_16x16x32_bf16 v[110:113], v[150:153], v[210:213], v[110:113]
	v_mfma_f32_16x16x32_bf16 v[102:105], v[158:161], v[210:213], v[102:105]
	v_mfma_f32_16x16x32_bf16 v[94:97], v[150:153], v[218:221], v[94:97]
	v_mfma_f32_16x16x32_bf16 v[86:89], v[158:161], v[218:221], v[86:89]
	v_mfma_f32_16x16x32_bf16 v[78:81], v[150:153], v[226:229], v[78:81]
	v_mfma_f32_16x16x32_bf16 v[70:73], v[158:161], v[226:229], v[70:73]
	v_mfma_f32_16x16x32_bf16 v[122:125], v[162:165], v[198:201], v[122:125]
	v_mfma_f32_16x16x32_bf16 v[114:117], v[190:193], v[198:201], v[114:117]
	v_mfma_f32_16x16x32_bf16 v[106:109], v[162:165], v[206:209], v[106:109]
	v_mfma_f32_16x16x32_bf16 v[98:101], v[190:193], v[206:209], v[98:101]
	v_mfma_f32_16x16x32_bf16 v[90:93], v[162:165], v[214:217], v[90:93]
	v_mfma_f32_16x16x32_bf16 v[82:85], v[190:193], v[214:217], v[82:85]
	v_mfma_f32_16x16x32_bf16 v[74:77], v[162:165], v[222:225], v[74:77]
	v_mfma_f32_16x16x32_bf16 v[66:69], v[190:193], v[222:225], v[66:69]
	v_mfma_f32_16x16x32_bf16 v[122:125], v[166:169], v[202:205], v[122:125]
	v_mfma_f32_16x16x32_bf16 v[114:117], v[194:197], v[202:205], v[114:117]
	v_mfma_f32_16x16x32_bf16 v[106:109], v[166:169], v[210:213], v[106:109]
	v_mfma_f32_16x16x32_bf16 v[98:101], v[194:197], v[210:213], v[98:101]
	v_mfma_f32_16x16x32_bf16 v[90:93], v[166:169], v[218:221], v[90:93]
	v_mfma_f32_16x16x32_bf16 v[82:85], v[194:197], v[218:221], v[82:85]
	v_mfma_f32_16x16x32_bf16 v[74:77], v[166:169], v[226:229], v[74:77]
	v_mfma_f32_16x16x32_bf16 v[66:69], v[194:197], v[226:229], v[66:69]
	s_setprio 0
	s_barrier
; #define PG8_STAGE(bufoff, gbase, voff) do { _Pragma("unroll") for (int _i = 0; _i < 2; ++_i) \
;         __builtin_amdgcn_global_load_lds((const unsigned*)((const char*)(gbase) + (voff)[_i]), (LAS unsigned*)(lds + (bufoff) + ldsw + _i * 8192), 16, 0, 0); } while (0)
; #define PG8_LDA(dst, b, h) do { _Pragma("unroll") for (int m = 0; m < 4; ++m) _Pragma("unroll") for (int k = 0; k < 2; ++k) dst[m][k] = *(const LAS bf16x8*)(lds + PG8_SA(b, h) + aoff + m * 2048 + k * 1024); } while (0)
; #define PG8_MMA(ai, bj, At, Bt) do { __builtin_amdgcn_s_setprio(1); _Pragma("unroll") for (int m = 0; m < 4; ++m) _Pragma("unroll") for (int n = 0; n < 2; ++n) _Pragma("unroll") for (int k = 0; k < 2; ++k) \
;         acc[ai][bj][m][n] = __builtin_amdgcn_mfma_f32_16x16x32_bf16(Bt[n][k], At[m][k], acc[ai][bj][m][n], 0, 0, 0); __builtin_amdgcn_s_setprio(0); } while (0)
; #define PG8_WAIT_V(n) asm volatile("s_waitcnt vmcnt(" #n ")" ::: "memory")
; #define PG8_WAIT_L(n) asm volatile("s_waitcnt lgkmcnt(" #n ")" ::: "memory")
; #define PG8_BAR __builtin_amdgcn_s_barrier()
; #define PG8_SCHED __builtin_amdgcn_sched_barrier(0)
; template <class Epi>
; __device__ __forceinline__ void gemm_phase(LAS unsigned char* lds, const Gemm g, const Epi& E) {
;     ...
;             PG8_LDA(At, 1, 1); PG8_STAGE(PG8_SB(1, 0), b3, voffA); PG8_STAGE(PG8_SB(1, 1), b3 + hstep, voffA); PG8_STAGE(PG8_SA(1, 0), a3, voffA);
;             PG8_WAIT_V(8); PG8_WAIT_L(0); PG8_BAR; PG8_MMA(1, 0, At, B0); PG8_MMA(1, 1, At, B1); PG8_BAR; PG8_SCHED;
	s_add_i32 s25, s25, s2
	v_lshl_add_u64 v[136:137], v[136:137], 0, s[80:81]
	s_mov_b32 m0, s25
	ds_read_b128 v[198:201], v145 offset:49152
	ds_read_b128 v[202:205], v145 offset:50176
	ds_read_b128 v[206:209], v145 offset:51200
	ds_read_b128 v[210:213], v145 offset:52224
	ds_read_b128 v[214:217], v145 offset:53248
	ds_read_b128 v[218:221], v145 offset:54272
	ds_read_b128 v[222:225], v145 offset:55296
	ds_read_b128 v[226:229], v145 offset:56320
	global_load_lds_dwordx4 v[136:137], off
	s_add_i32 m0, s25, 0x2000
	s_add_u32 s4, s4, 0x40080
	v_lshl_add_u64 v[136:137], v[230:231], 0, s[80:81]
	s_addc_u32 s5, s5, 0
	s_add_i32 s25, s72, s2
	global_load_lds_dwordx4 v[136:137], off
	v_lshl_add_u64 v[136:137], s[4:5], 0, v[0:1]
	s_mov_b32 m0, s25
	s_nop 0
	global_load_lds_dwordx4 v[136:137], off
	v_lshl_add_u64 v[136:137], s[4:5], 0, v[130:131]
	s_add_i32 m0, s25, 0x2000
	s_nop 0
	global_load_lds_dwordx4 v[136:137], off
	v_lshl_add_u64 v[136:137], v[232:233], 0, s[80:81]
	s_mov_b32 m0, s75
	s_nop 0
	global_load_lds_dwordx4 v[136:137], off
	v_lshl_add_u64 v[136:137], v[234:235], 0, s[80:81]
	s_mov_b32 m0, s76
	s_nop 0
	global_load_lds_dwordx4 v[136:137], off
	s_waitcnt vmcnt(8)
	s_waitcnt lgkmcnt(0)
	s_barrier
	s_setprio 1
	s_waitcnt lgkmcnt(0)
	v_mfma_f32_16x16x32_bf16 v[62:65], v[146:149], v[198:201], v[62:65]
	v_mfma_f32_16x16x32_bf16 v[54:57], v[154:157], v[198:201], v[54:57]
	v_mfma_f32_16x16x32_bf16 v[46:49], v[146:149], v[206:209], v[46:49]
	v_mfma_f32_16x16x32_bf16 v[38:41], v[154:157], v[206:209], v[38:41]
	v_mfma_f32_16x16x32_bf16 v[30:33], v[146:149], v[214:217], v[30:33]
	v_mfma_f32_16x16x32_bf16 v[22:25], v[154:157], v[214:217], v[22:25]
	v_mfma_f32_16x16x32_bf16 v[14:17], v[146:149], v[222:225], v[14:17]
	v_mfma_f32_16x16x32_bf16 v[6:9], v[154:157], v[222:225], v[6:9]
	v_mfma_f32_16x16x32_bf16 v[62:65], v[150:153], v[202:205], v[62:65]
	v_mfma_f32_16x16x32_bf16 v[54:57], v[158:161], v[202:205], v[54:57]
	v_mfma_f32_16x16x32_bf16 v[46:49], v[150:153], v[210:213], v[46:49]
	v_mfma_f32_16x16x32_bf16 v[38:41], v[158:161], v[210:213], v[38:41]
	v_mfma_f32_16x16x32_bf16 v[30:33], v[150:153], v[218:221], v[30:33]
	v_mfma_f32_16x16x32_bf16 v[22:25], v[158:161], v[218:221], v[22:25]
	v_mfma_f32_16x16x32_bf16 v[14:17], v[150:153], v[226:229], v[14:17]
	v_mfma_f32_16x16x32_bf16 v[6:9], v[158:161], v[226:229], v[6:9]
	v_mfma_f32_16x16x32_bf16 v[58:61], v[162:165], v[198:201], v[58:61]
	v_mfma_f32_16x16x32_bf16 v[50:53], v[190:193], v[198:201], v[50:53]
	v_mfma_f32_16x16x32_bf16 v[42:45], v[162:165], v[206:209], v[42:45]
	v_mfma_f32_16x16x32_bf16 v[34:37], v[190:193], v[206:209], v[34:37]
	v_mfma_f32_16x16x32_bf16 v[26:29], v[162:165], v[214:217], v[26:29]
	v_mfma_f32_16x16x32_bf16 v[18:21], v[190:193], v[214:217], v[18:21]
	v_mfma_f32_16x16x32_bf16 v[10:13], v[162:165], v[222:225], v[10:13]
	v_mfma_f32_16x16x32_bf16 v[2:5], v[190:193], v[222:225], v[2:5]
	v_mfma_f32_16x16x32_bf16 v[58:61], v[166:169], v[202:205], v[58:61]
	v_mfma_f32_16x16x32_bf16 v[50:53], v[194:197], v[202:205], v[50:53]
	v_mfma_f32_16x16x32_bf16 v[42:45], v[166:169], v[210:213], v[42:45]
	v_mfma_f32_16x16x32_bf16 v[34:37], v[194:197], v[210:213], v[34:37]
	v_mfma_f32_16x16x32_bf16 v[26:29], v[166:169], v[218:221], v[26:29]
	v_mfma_f32_16x16x32_bf16 v[18:21], v[194:197], v[218:221], v[18:21]
	v_mfma_f32_16x16x32_bf16 v[10:13], v[166:169], v[226:229], v[10:13]
	v_mfma_f32_16x16x32_bf16 v[2:5], v[194:197], v[226:229], v[2:5]
	s_setprio 0
	s_barrier
	s_add_u32 s68, s68, 0x100
	s_addc_u32 s69, s69, 0
	s_add_u32 s93, s93, 0x100
	s_addc_u32 vcc_lo, vcc_lo, 0
	s_cmp_ge_i32 vcc_hi, s37
	s_mov_b32 s4, vcc_hi
	s_cbranch_scc0 .LBB0_441

; #define PG8_STAGE(bufoff, gbase, voff) do { _Pragma("unroll") for (int _i = 0; _i < 2; ++_i) \
;         __builtin_amdgcn_global_load_lds((const unsigned*)((const char*)(gbase) + (voff)[_i]), (LAS unsigned*)(lds + (bufoff) + ldsw + _i * 8192), 16, 0, 0); } while (0)
; #define PG8_LDA(dst, b, h) do { _Pragma("unroll") for (int m = 0; m < 4; ++m) _Pragma("unroll") for (int k = 0; k < 2; ++k) dst[m][k] = *(const LAS bf16x8*)(lds + PG8_SA(b, h) + aoff + m * 2048 + k * 1024); } while (0)
; #define PG8_LDB(dst, b, h) do { _Pragma("unroll") for (int n = 0; n < 2; ++n) _Pragma("unroll") for (int k = 0; k < 2; ++k) dst[n][k] = *(const LAS bf16x8*)(lds + PG8_SB(b, h) + boff + n * 2048 + k * 1024); } while (0)
; #define PG8_MMA(ai, bj, At, Bt) do { __builtin_amdgcn_s_setprio(1); _Pragma("unroll") for (int m = 0; m < 4; ++m) _Pragma("unroll") for (int n = 0; n < 2; ++n) _Pragma("unroll") for (int k = 0; k < 2; ++k) \
;         acc[ai][bj][m][n] = __builtin_amdgcn_mfma_f32_16x16x32_bf16(Bt[n][k], At[m][k], acc[ai][bj][m][n], 0, 0, 0); __builtin_amdgcn_s_setprio(0); } while (0)
; #define PG8_WAIT_V(n) asm volatile("s_waitcnt vmcnt(" #n ")" ::: "memory")
; #define PG8_WAIT_L(n) asm volatile("s_waitcnt lgkmcnt(" #n ")" ::: "memory")
; #define PG8_BAR __builtin_amdgcn_s_barrier()
; #define PG8_SCHED __builtin_amdgcn_sched_barrier(0)
; template <class Epi>
; __device__ __forceinline__ void gemm_phase(LAS unsigned char* lds, const Gemm g, const Epi& E) {
;     ...
;             const bool last = (t == nt - 2);
;             const char* a1 = cA + (size_t)(t + 1) * kstep;
;             const char* a2 = last ? nA : cA + (size_t)(t + 2) * kstep; const char* b2 = last ? nB : cB + (size_t)(t + 2) * kstep;
;             const char* a3 = a2 + kstep; const char* b3 = b2 + kstep;
;             PG8_LDB(B0, 0, 0); PG8_LDB(B1, 0, 1); PG8_SCHED; PG8_LDA(At, 0, 0); PG8_STAGE(PG8_SA(1, 1), a1 + hstep, voffA);
;             PG8_WAIT_V(8); PG8_WAIT_L(0); PG8_BAR; PG8_MMA(0, 0, At, B0); PG8_MMA(0, 1, At, B1); PG8_BAR; PG8_SCHED;
;             PG8_LDA(At, 0, 1); PG8_STAGE(PG8_SB(0, 0), b2, voffA); PG8_STAGE(PG8_SB(0, 1), b2 + hstep, voffA); PG8_STAGE(PG8_SA(0, 0), a2, voffA);
;             PG8_WAIT_V(8); PG8_WAIT_L(0); PG8_BAR; PG8_MMA(1, 0, At, B0); PG8_MMA(1, 1, At, B1); PG8_BAR; PG8_SCHED;
.LBB0_473:
	s_add_i32 s61, s4, 2
	s_add_u32 s5, s10, 0xfffc0080
	s_addc_u32 s25, s11, -1
	s_cmp_eq_u32 s2, s4
	s_cselect_b32 s73, s67, s25
	s_cselect_b32 s72, s66, s5
	v_add_u32_e32 v0, s21, v160
	s_cselect_b32 s5, s69, s45
	s_cselect_b32 s4, s68, s15
	s_add_i32 s25, 0, 0x14000
	ds_read_b128 v[146:149], v0
	ds_read_b128 v[150:153], v0 offset:1024
	ds_read_b128 v[154:157], v0 offset:2048
	ds_read_b128 v[162:165], v0 offset:3072
	v_add_u32_e32 v0, s25, v160
	ds_read_b128 v[166:169], v0
	ds_read_b128 v[190:193], v0 offset:1024
	ds_read_b128 v[194:197], v0 offset:2048
	ds_read_b128 v[198:201], v0 offset:3072
	v_lshl_add_u64 v[2:3], s[10:11], 0, v[136:137]
	s_add_i32 m0, s7, 0xc000
	ds_read_b128 v[202:205], v161
	ds_read_b128 v[206:209], v161 offset:1024
	ds_read_b128 v[210:213], v161 offset:2048
	ds_read_b128 v[214:217], v161 offset:3072
	ds_read_b128 v[218:221], v161 offset:4096
	ds_read_b128 v[222:225], v161 offset:5120
	ds_read_b128 v[226:229], v161 offset:6144
	ds_read_b128 v[230:233], v161 offset:7168
	global_load_lds_dwordx4 v[2:3], off
	v_lshl_add_u64 v[2:3], s[10:11], 0, v[144:145]
	s_add_i32 m0, s7, 0xe000
	s_nop 0
	global_load_lds_dwordx4 v[2:3], off
	s_waitcnt vmcnt(8)
	s_waitcnt lgkmcnt(0)
	s_barrier
	s_setprio 1
	s_waitcnt lgkmcnt(0)
	v_mfma_f32_16x16x32_bf16 v[128:131], v[146:149], v[202:205], v[128:131]
	v_mfma_f32_16x16x32_bf16 v[124:127], v[154:157], v[202:205], v[124:127]
	v_mfma_f32_16x16x32_bf16 v[120:123], v[146:149], v[210:213], v[120:123]
	v_mfma_f32_16x16x32_bf16 v[116:119], v[154:157], v[210:213], v[116:119]
	v_mfma_f32_16x16x32_bf16 v[112:115], v[146:149], v[218:221], v[112:115]
	v_mfma_f32_16x16x32_bf16 v[108:111], v[154:157], v[218:221], v[108:111]
	v_mfma_f32_16x16x32_bf16 v[104:107], v[146:149], v[226:229], v[104:107]
	v_mfma_f32_16x16x32_bf16 v[100:103], v[154:157], v[226:229], v[100:103]
	v_mfma_f32_16x16x32_bf16 v[128:131], v[150:153], v[206:209], v[128:131]
	v_mfma_f32_16x16x32_bf16 v[124:127], v[162:165], v[206:209], v[124:127]
	v_mfma_f32_16x16x32_bf16 v[120:123], v[150:153], v[214:217], v[120:123]
	v_mfma_f32_16x16x32_bf16 v[116:119], v[162:165], v[214:217], v[116:119]
	v_mfma_f32_16x16x32_bf16 v[112:115], v[150:153], v[222:225], v[112:115]
	v_mfma_f32_16x16x32_bf16 v[108:111], v[162:165], v[222:225], v[108:111]
	v_mfma_f32_16x16x32_bf16 v[104:107], v[150:153], v[230:233], v[104:107]
	v_mfma_f32_16x16x32_bf16 v[100:103], v[162:165], v[230:233], v[100:103]
	v_mfma_f32_16x16x32_bf16 v[96:99], v[166:169], v[202:205], v[96:99]
	v_mfma_f32_16x16x32_bf16 v[92:95], v[194:197], v[202:205], v[92:95]
	v_mfma_f32_16x16x32_bf16 v[88:91], v[166:169], v[210:213], v[88:91]
	v_mfma_f32_16x16x32_bf16 v[84:87], v[194:197], v[210:213], v[84:87]
	v_mfma_f32_16x16x32_bf16 v[80:83], v[166:169], v[218:221], v[80:83]
	v_mfma_f32_16x16x32_bf16 v[76:79], v[194:197], v[218:221], v[76:79]
	v_mfma_f32_16x16x32_bf16 v[72:75], v[166:169], v[226:229], v[72:75]
	v_mfma_f32_16x16x32_bf16 v[68:71], v[194:197], v[226:229], v[68:71]
	v_mfma_f32_16x16x32_bf16 v[96:99], v[190:193], v[206:209], v[96:99]
	v_mfma_f32_16x16x32_bf16 v[92:95], v[198:201], v[206:209], v[92:95]
	v_mfma_f32_16x16x32_bf16 v[88:91], v[190:193], v[214:217], v[88:91]
	v_mfma_f32_16x16x32_bf16 v[84:87], v[198:201], v[214:217], v[84:87]
	v_mfma_f32_16x16x32_bf16 v[80:83], v[190:193], v[222:225], v[80:83]
	v_mfma_f32_16x16x32_bf16 v[76:79], v[198:201], v[222:225], v[76:79]
	v_mfma_f32_16x16x32_bf16 v[72:75], v[190:193], v[230:233], v[72:75]
	v_mfma_f32_16x16x32_bf16 v[68:71], v[198:201], v[230:233], v[68:71]
	s_setprio 0
	s_barrier
	s_add_i32 s63, s21, s20
	v_lshl_add_u64 v[158:159], s[4:5], 0, v[134:135]
	s_mov_b32 m0, s63
	ds_read_b128 v[202:205], v161 offset:16384
	ds_read_b128 v[206:209], v161 offset:17408
	ds_read_b128 v[210:213], v161 offset:18432
	ds_read_b128 v[214:217], v161 offset:19456
	ds_read_b128 v[218:221], v161 offset:20480
	ds_read_b128 v[222:225], v161 offset:21504
	ds_read_b128 v[226:229], v161 offset:22528
	ds_read_b128 v[230:233], v161 offset:23552
	global_load_lds_dwordx4 v[158:159], off
	s_add_i32 m0, s63, 0x2000
	s_add_u32 vcc_lo, s4, 0x40000
	v_lshl_add_u64 v[234:235], s[4:5], 0, v[132:133]
	s_addc_u32 vcc_hi, s5, 0
	s_add_i32 s25, s25, s20
	global_load_lds_dwordx4 v[234:235], off
	v_lshl_add_u64 v[2:3], vcc, 0, v[134:135]
	s_mov_b32 m0, s25
	v_lshl_add_u64 v[236:237], s[72:73], 0, v[134:135]
	global_load_lds_dwordx4 v[2:3], off
	v_lshl_add_u64 v[2:3], vcc, 0, v[132:133]
	s_add_i32 m0, s25, 0x2000
	v_lshl_add_u64 v[238:239], s[72:73], 0, v[132:133]
	global_load_lds_dwordx4 v[2:3], off
	s_mov_b32 m0, s7
	s_nop 0
	global_load_lds_dwordx4 v[236:237], off
	s_mov_b32 m0, s13
	s_nop 0
	global_load_lds_dwordx4 v[238:239], off
	s_waitcnt vmcnt(8)
	s_waitcnt lgkmcnt(0)
	s_barrier
; #define PG8_STAGE(bufoff, gbase, voff) do { _Pragma("unroll") for (int _i = 0; _i < 2; ++_i) \
;         __builtin_amdgcn_global_load_lds((const unsigned*)((const char*)(gbase) + (voff)[_i]), (LAS unsigned*)(lds + (bufoff) + ldsw + _i * 8192), 16, 0, 0); } while (0)
; #define PG8_LDA(dst, b, h) do { _Pragma("unroll") for (int m = 0; m < 4; ++m) _Pragma("unroll") for (int k = 0; k < 2; ++k) dst[m][k] = *(const LAS bf16x8*)(lds + PG8_SA(b, h) + aoff + m * 2048 + k * 1024); } while (0)
; #define PG8_LDB(dst, b, h) do { _Pragma("unroll") for (int n = 0; n < 2; ++n) _Pragma("unroll") for (int k = 0; k < 2; ++k) dst[n][k] = *(const LAS bf16x8*)(lds + PG8_SB(b, h) + boff + n * 2048 + k * 1024); } while (0)
; #define PG8_MMA(ai, bj, At, Bt) do { __builtin_amdgcn_s_setprio(1); _Pragma("unroll") for (int m = 0; m < 4; ++m) _Pragma("unroll") for (int n = 0; n < 2; ++n) _Pragma("unroll") for (int k = 0; k < 2; ++k) \
;         acc[ai][bj][m][n] = __builtin_amdgcn_mfma_f32_16x16x32_bf16(Bt[n][k], At[m][k], acc[ai][bj][m][n], 0, 0, 0); __builtin_amdgcn_s_setprio(0); } while (0)
; #define PG8_WAIT_V(n) asm volatile("s_waitcnt vmcnt(" #n ")" ::: "memory")
; #define PG8_WAIT_L(n) asm volatile("s_waitcnt lgkmcnt(" #n ")" ::: "memory")
; #define PG8_BAR __builtin_amdgcn_s_barrier()
; #define PG8_SCHED __builtin_amdgcn_sched_barrier(0)
; template <class Epi>
; __device__ __forceinline__ void gemm_phase(LAS unsigned char* lds, const Gemm g, const Epi& E) {
;     ...
;             PG8_WAIT_V(8); PG8_WAIT_L(0); PG8_BAR; PG8_MMA(1, 0, At, B0); PG8_MMA(1, 1, At, B1); PG8_BAR; PG8_SCHED;
;             PG8_LDB(B0, 1, 0); PG8_LDB(B1, 1, 1); PG8_SCHED; PG8_LDA(At, 1, 0); PG8_STAGE(PG8_SA(0, 1), a2 + hstep, voffA);
;             PG8_WAIT_V(8); PG8_WAIT_L(0); PG8_BAR; PG8_MMA(0, 0, At, B0); PG8_MMA(0, 1, At, B1); PG8_BAR; PG8_SCHED;
	s_setprio 1
	s_waitcnt lgkmcnt(0)
	v_mfma_f32_16x16x32_bf16 v[64:67], v[146:149], v[202:205], v[64:67]
	v_mfma_f32_16x16x32_bf16 v[60:63], v[154:157], v[202:205], v[60:63]
	v_mfma_f32_16x16x32_bf16 v[56:59], v[146:149], v[210:213], v[56:59]
	v_mfma_f32_16x16x32_bf16 v[52:55], v[154:157], v[210:213], v[52:55]
	v_mfma_f32_16x16x32_bf16 v[48:51], v[146:149], v[218:221], v[48:51]
	v_mfma_f32_16x16x32_bf16 v[44:47], v[154:157], v[218:221], v[44:47]
	v_mfma_f32_16x16x32_bf16 v[40:43], v[146:149], v[226:229], v[40:43]
	v_mfma_f32_16x16x32_bf16 v[36:39], v[154:157], v[226:229], v[36:39]
	v_mfma_f32_16x16x32_bf16 v[64:67], v[150:153], v[206:209], v[64:67]
	v_mfma_f32_16x16x32_bf16 v[60:63], v[162:165], v[206:209], v[60:63]
	v_mfma_f32_16x16x32_bf16 v[56:59], v[150:153], v[214:217], v[56:59]
	v_mfma_f32_16x16x32_bf16 v[52:55], v[162:165], v[214:217], v[52:55]
	v_mfma_f32_16x16x32_bf16 v[48:51], v[150:153], v[222:225], v[48:51]
	v_mfma_f32_16x16x32_bf16 v[44:47], v[162:165], v[222:225], v[44:47]
	v_mfma_f32_16x16x32_bf16 v[40:43], v[150:153], v[230:233], v[40:43]
	v_mfma_f32_16x16x32_bf16 v[36:39], v[162:165], v[230:233], v[36:39]
	v_mfma_f32_16x16x32_bf16 v[32:35], v[166:169], v[202:205], v[32:35]
	v_mfma_f32_16x16x32_bf16 v[28:31], v[194:197], v[202:205], v[28:31]
	v_mfma_f32_16x16x32_bf16 v[24:27], v[166:169], v[210:213], v[24:27]
	v_mfma_f32_16x16x32_bf16 v[20:23], v[194:197], v[210:213], v[20:23]
	v_mfma_f32_16x16x32_bf16 v[16:19], v[166:169], v[218:221], v[16:19]
	v_mfma_f32_16x16x32_bf16 v[12:15], v[194:197], v[218:221], v[12:15]
	v_mfma_f32_16x16x32_bf16 v[8:11], v[166:169], v[226:229], v[8:11]
	v_mfma_f32_16x16x32_bf16 v[2:5], v[194:197], v[226:229], v[4:7]
	v_mfma_f32_16x16x32_bf16 v[32:35], v[190:193], v[206:209], v[32:35]
	v_mfma_f32_16x16x32_bf16 v[28:31], v[198:201], v[206:209], v[28:31]
	v_mfma_f32_16x16x32_bf16 v[24:27], v[190:193], v[214:217], v[24:27]
	v_mfma_f32_16x16x32_bf16 v[20:23], v[198:201], v[214:217], v[20:23]
	v_mfma_f32_16x16x32_bf16 v[16:19], v[190:193], v[222:225], v[16:19]
	v_mfma_f32_16x16x32_bf16 v[12:15], v[198:201], v[222:225], v[12:15]
	v_mfma_f32_16x16x32_bf16 v[8:11], v[190:193], v[230:233], v[8:11]
	v_mfma_f32_16x16x32_bf16 v[2:5], v[198:201], v[230:233], v[2:5]
	s_setprio 0
	s_barrier
	s_add_i32 s25, 0, 0x18000
	v_add_u32_e32 v0, s25, v160
	s_add_i32 s63, 0, 0x1c000
	ds_read_b128 v[146:149], v0
	ds_read_b128 v[150:153], v0 offset:1024
	ds_read_b128 v[154:157], v0 offset:2048
	ds_read_b128 v[162:165], v0 offset:3072
	v_add_u32_e32 v0, s63, v160
	ds_read_b128 v[166:169], v0
	ds_read_b128 v[190:193], v0 offset:1024
	ds_read_b128 v[194:197], v0 offset:2048
	ds_read_b128 v[198:201], v0 offset:3072
	s_add_u32 s72, s72, 0x40000
	s_addc_u32 s73, s73, 0
	s_mov_b32 m0, s75
	v_lshl_add_u64 v[6:7], s[72:73], 0, v[134:135]
	ds_read_b128 v[202:205], v161 offset:32768
	ds_read_b128 v[206:209], v161 offset:33792
	ds_read_b128 v[210:213], v161 offset:34816
	ds_read_b128 v[214:217], v161 offset:35840
	ds_read_b128 v[218:221], v161 offset:36864
	ds_read_b128 v[222:225], v161 offset:37888
	ds_read_b128 v[226:229], v161 offset:38912
	ds_read_b128 v[230:233], v161 offset:39936
	global_load_lds_dwordx4 v[6:7], off
	v_lshl_add_u64 v[6:7], s[72:73], 0, v[132:133]
	s_mov_b32 m0, s76
	s_nop 0
	global_load_lds_dwordx4 v[6:7], off
	s_waitcnt vmcnt(8)
	s_waitcnt lgkmcnt(0)
	s_barrier
	s_setprio 1
	s_waitcnt lgkmcnt(0)
	v_mfma_f32_16x16x32_bf16 v[128:131], v[146:149], v[202:205], v[128:131]
	v_mfma_f32_16x16x32_bf16 v[124:127], v[154:157], v[202:205], v[124:127]
	v_mfma_f32_16x16x32_bf16 v[120:123], v[146:149], v[210:213], v[120:123]
	v_mfma_f32_16x16x32_bf16 v[116:119], v[154:157], v[210:213], v[116:119]
	v_mfma_f32_16x16x32_bf16 v[112:115], v[146:149], v[218:221], v[112:115]
	v_mfma_f32_16x16x32_bf16 v[108:111], v[154:157], v[218:221], v[108:111]
	v_mfma_f32_16x16x32_bf16 v[104:107], v[146:149], v[226:229], v[104:107]
	v_mfma_f32_16x16x32_bf16 v[100:103], v[154:157], v[226:229], v[100:103]
	v_mfma_f32_16x16x32_bf16 v[128:131], v[150:153], v[206:209], v[128:131]
	v_mfma_f32_16x16x32_bf16 v[124:127], v[162:165], v[206:209], v[124:127]
	v_mfma_f32_16x16x32_bf16 v[120:123], v[150:153], v[214:217], v[120:123]
	v_mfma_f32_16x16x32_bf16 v[116:119], v[162:165], v[214:217], v[116:119]
	v_mfma_f32_16x16x32_bf16 v[112:115], v[150:153], v[222:225], v[112:115]
	v_mfma_f32_16x16x32_bf16 v[108:111], v[162:165], v[222:225], v[108:111]
	v_mfma_f32_16x16x32_bf16 v[104:107], v[150:153], v[230:233], v[104:107]
	v_mfma_f32_16x16x32_bf16 v[100:103], v[162:165], v[230:233], v[100:103]
	v_mfma_f32_16x16x32_bf16 v[96:99], v[166:169], v[202:205], v[96:99]
	v_mfma_f32_16x16x32_bf16 v[92:95], v[194:197], v[202:205], v[92:95]
	v_mfma_f32_16x16x32_bf16 v[88:91], v[166:169], v[210:213], v[88:91]
	v_mfma_f32_16x16x32_bf16 v[84:87], v[194:197], v[210:213], v[84:87]
	v_mfma_f32_16x16x32_bf16 v[80:83], v[166:169], v[218:221], v[80:83]
	v_mfma_f32_16x16x32_bf16 v[76:79], v[194:197], v[218:221], v[76:79]
	v_mfma_f32_16x16x32_bf16 v[72:75], v[166:169], v[226:229], v[72:75]
	v_mfma_f32_16x16x32_bf16 v[68:71], v[194:197], v[226:229], v[68:71]
	v_mfma_f32_16x16x32_bf16 v[96:99], v[190:193], v[206:209], v[96:99]
	v_mfma_f32_16x16x32_bf16 v[92:95], v[198:201], v[206:209], v[92:95]
	v_mfma_f32_16x16x32_bf16 v[88:91], v[190:193], v[214:217], v[88:91]
	v_mfma_f32_16x16x32_bf16 v[84:87], v[198:201], v[214:217], v[84:87]
	v_mfma_f32_16x16x32_bf16 v[80:83], v[190:193], v[222:225], v[80:83]
	v_mfma_f32_16x16x32_bf16 v[76:79], v[198:201], v[222:225], v[76:79]
	v_mfma_f32_16x16x32_bf16 v[72:75], v[190:193], v[230:233], v[72:75]
	v_mfma_f32_16x16x32_bf16 v[68:71], v[198:201], v[230:233], v[68:71]
	s_setprio 0
	s_barrier
; #define PG8_STAGE(bufoff, gbase, voff) do { _Pragma("unroll") for (int _i = 0; _i < 2; ++_i) \
;         __builtin_amdgcn_global_load_lds((const unsigned*)((const char*)(gbase) + (voff)[_i]), (LAS unsigned*)(lds + (bufoff) + ldsw + _i * 8192), 16, 0, 0); } while (0)
; #define PG8_LDA(dst, b, h) do { _Pragma("unroll") for (int m = 0; m < 4; ++m) _Pragma("unroll") for (int k = 0; k < 2; ++k) dst[m][k] = *(const LAS bf16x8*)(lds + PG8_SA(b, h) + aoff + m * 2048 + k * 1024); } while (0)
; #define PG8_MMA(ai, bj, At, Bt) do { __builtin_amdgcn_s_setprio(1); _Pragma("unroll") for (int m = 0; m < 4; ++m) _Pragma("unroll") for (int n = 0; n < 2; ++n) _Pragma("unroll") for (int k = 0; k < 2; ++k) \
;         acc[ai][bj][m][n] = __builtin_amdgcn_mfma_f32_16x16x32_bf16(Bt[n][k], At[m][k], acc[ai][bj][m][n], 0, 0, 0); __builtin_amdgcn_s_setprio(0); } while (0)
; #define PG8_WAIT_V(n) asm volatile("s_waitcnt vmcnt(" #n ")" ::: "memory")
; #define PG8_WAIT_L(n) asm volatile("s_waitcnt lgkmcnt(" #n ")" ::: "memory")
; #define PG8_BAR __builtin_amdgcn_s_barrier()
; #define PG8_SCHED __builtin_amdgcn_sched_barrier(0)
; template <class Epi>
; __device__ __forceinline__ void gemm_phase(LAS unsigned char* lds, const Gemm g, const Epi& E) {
;     ...
;             PG8_LDA(At, 1, 1); PG8_STAGE(PG8_SB(1, 0), b3, voffA); PG8_STAGE(PG8_SB(1, 1), b3 + hstep, voffA); PG8_STAGE(PG8_SA(1, 0), a3, voffA);
;             PG8_WAIT_V(8); PG8_WAIT_L(0); PG8_BAR; PG8_MMA(1, 0, At, B0); PG8_MMA(1, 1, At, B1); PG8_BAR; PG8_SCHED;
	s_add_i32 s25, s25, s20
	v_lshl_add_u64 v[6:7], v[158:159], 0, s[80:81]
	s_mov_b32 m0, s25
	ds_read_b128 v[202:205], v161 offset:49152
	ds_read_b128 v[206:209], v161 offset:50176
	ds_read_b128 v[210:213], v161 offset:51200
	ds_read_b128 v[214:217], v161 offset:52224
	ds_read_b128 v[218:221], v161 offset:53248
	ds_read_b128 v[222:225], v161 offset:54272
	ds_read_b128 v[226:229], v161 offset:55296
	ds_read_b128 v[230:233], v161 offset:56320
	global_load_lds_dwordx4 v[6:7], off
	s_add_i32 m0, s25, 0x2000
	s_add_u32 s4, s4, 0x40080
	v_lshl_add_u64 v[6:7], v[234:235], 0, s[80:81]
	s_addc_u32 s5, s5, 0
	s_add_i32 s25, s63, s20
	global_load_lds_dwordx4 v[6:7], off
	v_lshl_add_u64 v[6:7], s[4:5], 0, v[134:135]
	s_mov_b32 m0, s25
	s_nop 0
	global_load_lds_dwordx4 v[6:7], off
	v_lshl_add_u64 v[6:7], s[4:5], 0, v[132:133]
	s_add_i32 m0, s25, 0x2000
	s_nop 0
	global_load_lds_dwordx4 v[6:7], off
	v_lshl_add_u64 v[6:7], v[236:237], 0, s[80:81]
	s_mov_b32 m0, s79
	s_nop 0
	global_load_lds_dwordx4 v[6:7], off
	v_lshl_add_u64 v[6:7], v[238:239], 0, s[80:81]
	s_mov_b32 m0, s82
	s_nop 0
	global_load_lds_dwordx4 v[6:7], off
	s_waitcnt vmcnt(8)
	s_waitcnt lgkmcnt(0)
	s_barrier
	s_setprio 1
	s_waitcnt lgkmcnt(0)
	v_mfma_f32_16x16x32_bf16 v[64:67], v[146:149], v[202:205], v[64:67]
	v_mfma_f32_16x16x32_bf16 v[60:63], v[154:157], v[202:205], v[60:63]
	v_mfma_f32_16x16x32_bf16 v[56:59], v[146:149], v[210:213], v[56:59]
	v_mfma_f32_16x16x32_bf16 v[52:55], v[154:157], v[210:213], v[52:55]
	v_mfma_f32_16x16x32_bf16 v[48:51], v[146:149], v[218:221], v[48:51]
	v_mfma_f32_16x16x32_bf16 v[44:47], v[154:157], v[218:221], v[44:47]
	v_mfma_f32_16x16x32_bf16 v[40:43], v[146:149], v[226:229], v[40:43]
	v_mfma_f32_16x16x32_bf16 v[36:39], v[154:157], v[226:229], v[36:39]
	v_mfma_f32_16x16x32_bf16 v[64:67], v[150:153], v[206:209], v[64:67]
	v_mfma_f32_16x16x32_bf16 v[60:63], v[162:165], v[206:209], v[60:63]
	v_mfma_f32_16x16x32_bf16 v[56:59], v[150:153], v[214:217], v[56:59]
	v_mfma_f32_16x16x32_bf16 v[52:55], v[162:165], v[214:217], v[52:55]
	v_mfma_f32_16x16x32_bf16 v[48:51], v[150:153], v[222:225], v[48:51]
	v_mfma_f32_16x16x32_bf16 v[44:47], v[162:165], v[222:225], v[44:47]
	v_mfma_f32_16x16x32_bf16 v[40:43], v[150:153], v[230:233], v[40:43]
	v_mfma_f32_16x16x32_bf16 v[36:39], v[162:165], v[230:233], v[36:39]
	v_mfma_f32_16x16x32_bf16 v[32:35], v[166:169], v[202:205], v[32:35]
	v_mfma_f32_16x16x32_bf16 v[28:31], v[194:197], v[202:205], v[28:31]
	v_mfma_f32_16x16x32_bf16 v[24:27], v[166:169], v[210:213], v[24:27]
	v_mfma_f32_16x16x32_bf16 v[20:23], v[194:197], v[210:213], v[20:23]
	v_mfma_f32_16x16x32_bf16 v[16:19], v[166:169], v[218:221], v[16:19]
	v_mfma_f32_16x16x32_bf16 v[12:15], v[194:197], v[218:221], v[12:15]
	v_mfma_f32_16x16x32_bf16 v[6:9], v[166:169], v[226:229], v[8:11]
	v_mfma_f32_16x16x32_bf16 v[2:5], v[194:197], v[226:229], v[2:5]
	v_mfma_f32_16x16x32_bf16 v[32:35], v[190:193], v[206:209], v[32:35]
	v_mfma_f32_16x16x32_bf16 v[28:31], v[198:201], v[206:209], v[28:31]
	v_mfma_f32_16x16x32_bf16 v[24:27], v[190:193], v[214:217], v[24:27]
	v_mfma_f32_16x16x32_bf16 v[20:23], v[198:201], v[214:217], v[20:23]
	v_mfma_f32_16x16x32_bf16 v[16:19], v[190:193], v[222:225], v[16:19]
	v_mfma_f32_16x16x32_bf16 v[12:15], v[198:201], v[222:225], v[12:15]
	v_mfma_f32_16x16x32_bf16 v[8:11], v[190:193], v[230:233], v[6:9]
	v_mfma_f32_16x16x32_bf16 v[4:7], v[198:201], v[230:233], v[2:5]
	s_setprio 0
	s_barrier
	s_add_u32 s10, s10, 0x100
	s_addc_u32 s11, s11, 0
	s_add_u32 s15, s15, 0x100
	s_addc_u32 s45, s45, 0
	s_cmp_ge_i32 s61, s74
	s_mov_b32 s4, s61
	s_cbranch_scc0 .LBB0_473
